# speedup vs baseline: 1.0040x; 1.0040x over previous
.LBB0_579:
	s_ashr_i32 s4, s0, 6
	s_mul_hi_i32 s5, s4, 0x55555556
	s_lshr_b32 s6, s5, 31
	s_add_i32 s5, s5, s6
	s_mul_i32 s5, s5, 3
	s_sub_i32 s4, s4, s5
	s_mul_hi_i32 s5, s0, 0x2aaaaaab
	s_lshr_b32 s6, s5, 31
	s_ashr_i32 s5, s5, 5
	s_and_b32 s7, s0, 15
	s_add_i32 s6, s5, s6
	s_lshl_b32 s5, s4, 1
	s_lshr_b32 s22, s7, s5
	s_lshl_b32 s8, -1, s5
	s_andn2_b32 s13, s7, s8
	v_sub_co_u32_e64 v0, s[8:9], s22, 1
	s_ashr_i32 s7, s6, 31
	v_readfirstlane_b32 s10, v0
	s_lshl_b64 s[6:7], s[6:7], 11
	s_ashr_i32 s11, s10, 31
	s_add_i32 s12, s5, 7
	s_bfe_u32 s1, s0, 0x20004
	s_lshl_b64 s[10:11], s[10:11], s12
	s_or_b32 s6, s6, s13
	s_add_u32 s10, s6, s10
	s_addc_u32 s11, s7, s11
	s_lshl_b64 s[10:11], s[10:11], 11
	s_add_u32 s10, s60, s10
	s_addc_u32 s11, s61, s11
	s_lshl_b32 s13, s1, 8
	s_add_u32 s16, s10, s13
	v_mov_b32_e32 v14, v190
	s_addc_u32 s17, s11, 0
	v_mov_b32_e32 v115, v190
	s_and_b64 s[8:9], s[8:9], exec
	s_cselect_b32 s11, 0x80, 0
	v_and_b32_e32 v16, 15, v115
	v_ashrrev_i32_e32 v12, 4, v115
	v_lshlrev_b32_e32 v128, 4, v16
	v_lshl_add_u64 v[10:11], s[16:17], 0, v[128:129]
	v_cmp_le_i32_e32 vcc, s11, v12
	v_mov_b32_e32 v0, 0
	v_mov_b32_e32 v2, 0
	v_mov_b32_e32 v3, 0
	v_mov_b32_e32 v4, 0
	v_mov_b32_e32 v5, 0
	v_mov_b32_e32 v6, 0
	v_mov_b32_e32 v7, 0
	v_mov_b32_e32 v8, 0
	v_mov_b32_e32 v9, 0
	s_add_i32 s13, s5, 10
	v_mov_b32_e32 v22, 0
	v_mov_b32_e32 v23, 0
	v_mov_b32_e32 v24, 0
	v_mov_b32_e32 v25, 0
	v_mov_b32_e32 v26, 0
	v_mov_b32_e32 v27, 0
	v_mov_b32_e32 v28, 0
	v_mov_b32_e32 v29, 0
	v_mov_b32_e32 v30, 0
	v_mov_b32_e32 v31, 0
	v_mov_b32_e32 v32, 0
	v_mov_b32_e32 v33, 0
	v_mov_b32_e32 v34, 0
	v_mov_b32_e32 v35, 0
	v_mov_b32_e32 v36, 0
	v_mov_b32_e32 v37, 0
	v_mov_b32_e32 v38, 0
	v_mov_b32_e32 v39, 0
	v_mov_b32_e32 v40, 0
	v_mov_b32_e32 v41, 0
	v_mov_b32_e32 v42, 0
	v_mov_b32_e32 v43, 0
	v_mov_b32_e32 v44, 0
	v_mov_b32_e32 v45, 0
	v_mov_b32_e32 v46, 0
	v_mov_b32_e32 v47, 0
	v_mov_b32_e32 v48, 0
	v_mov_b32_e32 v49, 0
	v_mov_b32_e32 v50, 0
	v_mov_b32_e32 v51, 0
	v_mov_b32_e32 v52, 0
	v_mov_b32_e32 v53, 0
	v_mov_b32_e32 v54, 0
	v_mov_b32_e32 v55, 0
	v_mov_b32_e32 v56, 0
	v_mov_b32_e32 v57, 0
	v_mov_b32_e32 v58, 0
	v_mov_b32_e32 v59, 0
	v_mov_b32_e32 v60, 0
	v_mov_b32_e32 v61, 0
	v_mov_b32_e32 v62, 0
	v_mov_b32_e32 v63, 0
	v_mov_b32_e32 v64, 0
	v_mov_b32_e32 v65, 0
	v_mov_b32_e32 v66, 0
	v_mov_b32_e32 v67, 0
	v_mov_b32_e32 v68, 0
	v_mov_b32_e32 v69, 0
	v_mov_b32_e32 v70, 0
	v_mov_b32_e32 v71, 0
	v_mov_b32_e32 v72, 0
	v_mov_b32_e32 v73, 0
	v_mov_b32_e32 v74, 0
	v_mov_b32_e32 v75, 0
	v_mov_b32_e32 v76, 0
	v_mov_b32_e32 v77, 0
	v_mov_b32_e32 v78, 0
	v_mov_b32_e32 v79, 0
	v_mov_b32_e32 v80, 0
	v_mov_b32_e32 v81, 0
	v_mov_b32_e32 v82, 0
	v_mov_b32_e32 v83, 0
	v_mov_b32_e32 v84, 0
	v_mov_b32_e32 v85, 0
	v_mov_b32_e32 v88, v12
	v_mov_b32_e32 v89, v129
	v_cmp_le_i32_e32 vcc, s11, v88
	s_and_saveexec_b64 s[8:9], vcc
	v_lshlrev_b64 v[86:87], s13, v[88:89]
	v_lshl_add_u64 v[86:87], v[86:87], 1, v[10:11]
	global_load_dwordx4 v[22:25], v[86:87], off
	global_load_dwordx4 v[26:29], v[86:87], off offset:1024
	s_or_b64 exec, exec, s[8:9]
	v_add_u32_e32 v88, 32, v12
	v_mov_b32_e32 v89, v129
	v_cmp_le_i32_e32 vcc, s11, v88
	s_and_saveexec_b64 s[8:9], vcc
	v_lshlrev_b64 v[86:87], s13, v[88:89]
	v_lshl_add_u64 v[86:87], v[86:87], 1, v[10:11]
	global_load_dwordx4 v[30:33], v[86:87], off
	global_load_dwordx4 v[34:37], v[86:87], off offset:1024
	s_or_b64 exec, exec, s[8:9]
	v_add_u32_e32 v88, 64, v12
	v_mov_b32_e32 v89, v129
	v_cmp_le_i32_e32 vcc, s11, v88
	s_and_saveexec_b64 s[8:9], vcc
	v_lshlrev_b64 v[86:87], s13, v[88:89]
	v_lshl_add_u64 v[86:87], v[86:87], 1, v[10:11]
	global_load_dwordx4 v[38:41], v[86:87], off
	global_load_dwordx4 v[42:45], v[86:87], off offset:1024
	s_or_b64 exec, exec, s[8:9]
	v_add_u32_e32 v88, 96, v12
	v_mov_b32_e32 v89, v129
	v_cmp_le_i32_e32 vcc, s11, v88
	s_and_saveexec_b64 s[8:9], vcc
	v_lshlrev_b64 v[86:87], s13, v[88:89]
	v_lshl_add_u64 v[86:87], v[86:87], 1, v[10:11]
	global_load_dwordx4 v[46:49], v[86:87], off
	global_load_dwordx4 v[50:53], v[86:87], off offset:1024
	s_or_b64 exec, exec, s[8:9]
	v_add_u32_e32 v88, 128, v12
	v_mov_b32_e32 v89, v129
	v_cmp_le_i32_e32 vcc, s11, v88
	s_and_saveexec_b64 s[8:9], vcc
	v_lshlrev_b64 v[86:87], s13, v[88:89]
	v_lshl_add_u64 v[86:87], v[86:87], 1, v[10:11]
	global_load_dwordx4 v[54:57], v[86:87], off
	global_load_dwordx4 v[58:61], v[86:87], off offset:1024
	s_or_b64 exec, exec, s[8:9]
	v_add_u32_e32 v88, 160, v12
	v_mov_b32_e32 v89, v129
	v_cmp_le_i32_e32 vcc, s11, v88
	s_and_saveexec_b64 s[8:9], vcc
	v_lshlrev_b64 v[86:87], s13, v[88:89]
	v_lshl_add_u64 v[86:87], v[86:87], 1, v[10:11]
	global_load_dwordx4 v[62:65], v[86:87], off
	global_load_dwordx4 v[66:69], v[86:87], off offset:1024
	s_or_b64 exec, exec, s[8:9]
	v_add_u32_e32 v88, 192, v12
	v_mov_b32_e32 v89, v129
	v_cmp_le_i32_e32 vcc, s11, v88
	s_and_saveexec_b64 s[8:9], vcc
	v_lshlrev_b64 v[86:87], s13, v[88:89]
	v_lshl_add_u64 v[86:87], v[86:87], 1, v[10:11]
	global_load_dwordx4 v[70:73], v[86:87], off
	global_load_dwordx4 v[74:77], v[86:87], off offset:1024
	s_or_b64 exec, exec, s[8:9]
	v_add_u32_e32 v88, 224, v12
	v_mov_b32_e32 v89, v129
	v_cmp_le_i32_e32 vcc, s11, v88
	s_and_saveexec_b64 s[8:9], vcc
	v_lshlrev_b64 v[86:87], s13, v[88:89]
	v_lshl_add_u64 v[86:87], v[86:87], 1, v[10:11]
	global_load_dwordx4 v[78:81], v[86:87], off
	global_load_dwordx4 v[82:85], v[86:87], off offset:1024
	s_or_b64 exec, exec, s[8:9]
	s_barrier
	v_xor_b32_e32 v1, v12, v115
	v_lshlrev_b32_e32 v1, 4, v1
	v_and_b32_e32 v1, 0xf0, v1
	v_add_u32_e32 v13, 0, v1
	v_lshrrev_b32_e32 v1, 1, v16
	v_lshlrev_b32_e32 v15, 1, v12
	v_bitop3_b32 v1, v15, v1, 6 bitop3:0x6c
	v_lshlrev_b32_e32 v15, 4, v115
	v_lshlrev_b32_e32 v1, 5, v1
	v_and_b32_e32 v15, 16, v15
	s_add_i32 s10, 0, 0x10000
	v_add3_u32 v15, s10, v1, v15
	v_lshlrev_b32_e32 v1, 8, v12
	v_add_u32_e32 v17, v13, v1
	v_add_u32_e32 v1, v15, v1
	v_add_u32_e32 v128, 32, v12
	s_waitcnt vmcnt(15)
	ds_write_b128 v17, v[22:25]
	s_waitcnt vmcnt(14)
	ds_write_b128 v1, v[26:29]
	v_cmp_le_i32_e32 vcc, s11, v128
	v_mov_b32_e32 v2, 0
	v_mov_b32_e32 v3, 0
	v_mov_b32_e32 v4, 0
	v_mov_b32_e32 v5, 0
	v_mov_b32_e32 v6, 0
	v_mov_b32_e32 v7, 0
	v_mov_b32_e32 v8, 0
	v_mov_b32_e32 v9, 0
	v_lshlrev_b32_e32 v1, 8, v128
	v_add_u32_e32 v17, v13, v1
	v_add_u32_e32 v1, v15, v1
	v_add_u32_e32 v128, 64, v12
	s_waitcnt vmcnt(13)
	ds_write_b128 v17, v[30:33]
	s_waitcnt vmcnt(12)
	ds_write_b128 v1, v[34:37]
	v_cmp_le_i32_e32 vcc, s11, v128
	v_mov_b32_e32 v1, 0
	v_mov_b32_e32 v2, 0
	v_mov_b32_e32 v3, 0
	v_mov_b32_e32 v4, 0
	v_mov_b32_e32 v5, 0
	v_mov_b32_e32 v6, 0
	v_mov_b32_e32 v7, 0
	v_lshlrev_b32_e32 v8, 8, v128
	v_add_u32_e32 v9, v13, v8
	s_waitcnt vmcnt(11)
	ds_write_b128 v9, v[38:41]
	v_add_u32_e32 v4, v15, v8
	v_add_u32_e32 v128, 0x60, v12
	s_waitcnt vmcnt(10)
	ds_write_b128 v4, v[42:45]
	v_cmp_le_i32_e32 vcc, s11, v128
	v_mov_b32_e32 v0, 0
	v_mov_b32_e32 v2, 0
	v_mov_b32_e32 v3, 0
	v_mov_b32_e32 v4, 0
	v_mov_b32_e32 v5, 0
	v_mov_b32_e32 v6, 0
	v_mov_b32_e32 v7, 0
	v_mov_b32_e32 v8, 0
	v_mov_b32_e32 v9, 0
	v_lshlrev_b32_e32 v1, 8, v128
	v_add_u32_e32 v17, v13, v1
	v_add_u32_e32 v1, v15, v1
	v_add_u32_e32 v128, 0x80, v12
	s_waitcnt vmcnt(9)
	ds_write_b128 v17, v[46:49]
	s_waitcnt vmcnt(8)
	ds_write_b128 v1, v[50:53]
	v_cmp_le_i32_e32 vcc, s11, v128
	v_mov_b32_e32 v1, 0
	v_mov_b32_e32 v2, 0
	v_mov_b32_e32 v3, 0
	v_mov_b32_e32 v4, 0
	v_mov_b32_e32 v5, 0
	v_mov_b32_e32 v6, 0
	v_mov_b32_e32 v7, 0
	v_lshlrev_b32_e32 v8, 8, v128
	v_add_u32_e32 v9, v13, v8
	s_waitcnt vmcnt(7)
	ds_write_b128 v9, v[54:57]
	v_add_u32_e32 v4, v15, v8
	v_add_u32_e32 v128, 0xa0, v12
	s_waitcnt vmcnt(6)
	ds_write_b128 v4, v[58:61]
	v_cmp_le_i32_e32 vcc, s11, v128
	v_mov_b32_e32 v0, 0
	v_mov_b32_e32 v2, 0
	v_mov_b32_e32 v3, 0
	v_mov_b32_e32 v4, 0
	v_mov_b32_e32 v5, 0
	v_mov_b32_e32 v6, 0
	v_mov_b32_e32 v7, 0
	v_mov_b32_e32 v8, 0
	v_mov_b32_e32 v9, 0
	v_lshlrev_b32_e32 v1, 8, v128
	v_add_u32_e32 v17, v13, v1
	v_add_u32_e32 v1, v15, v1
	v_add_u32_e32 v128, 0xc0, v12
	s_waitcnt vmcnt(5)
	ds_write_b128 v17, v[62:65]
	s_waitcnt vmcnt(4)
	ds_write_b128 v1, v[66:69]
	v_cmp_le_i32_e32 vcc, s11, v128
	v_mov_b32_e32 v1, 0
	v_mov_b32_e32 v2, 0
	v_mov_b32_e32 v3, 0
	v_mov_b32_e32 v4, 0
	v_mov_b32_e32 v5, 0
	v_mov_b32_e32 v6, 0
	v_mov_b32_e32 v7, 0
	v_lshlrev_b32_e32 v8, 8, v128
	v_add_u32_e32 v9, v13, v8
	s_waitcnt vmcnt(3)
	ds_write_b128 v9, v[70:73]
	v_add_u32_e32 v4, v15, v8
	v_add_u32_e32 v8, 0xe0, v12
	s_waitcnt vmcnt(2)
	ds_write_b128 v4, v[74:77]
	v_cmp_le_i32_e32 vcc, s11, v8
	v_mov_b32_e32 v0, 0
	v_mov_b32_e32 v1, 0
	v_mov_b32_e32 v2, 0
	v_mov_b32_e32 v3, 0
	v_mov_b32_e32 v4, 0
	v_mov_b32_e32 v5, 0
	v_mov_b32_e32 v6, 0
	v_mov_b32_e32 v7, 0
	s_lshl_b32 s1, s1, 1
	v_readlane_b32 s8, v240, 42
	s_add_i32 s1, s1, s8
	v_readlane_b32 s8, v240, 44
	v_mov_b64_e32 v[18:19], s[66:67]
	v_lshlrev_b32_e32 v8, 8, v8
	v_and_or_b32 v128, v14, 31, s8
	s_lshl_b64 s[8:9], s[22:23], s12
	s_add_u32 s6, s6, s8
	v_lshlrev_b64 v[10:11], s5, v[128:129]
	s_addc_u32 s7, s7, s9
	v_lshl_add_u64 v[10:11], s[6:7], 0, v[10:11]
	s_movk_i32 s5, 0x1800
	v_mad_u64_u32 v[18:19], s[6:7], v10, s5, v[18:19]
	v_mov_b32_e32 v12, v19
	v_mad_u64_u32 v[20:21], s[6:7], v11, s5, v[12:13]
	s_ashr_i32 s5, s4, 31
	s_lshl_b32 s6, s4, 10
	s_lshl_b64 s[4:5], s[4:5], 13
	v_lshl_add_u64 v[108:109], v[10:11], 0, s[4:5]
	v_lshlrev_b64 v[10:11], 11, v[108:109]
	s_lshl_b32 s22, s1, 8
	v_lshl_add_u64 v[10:11], s[90:91], 0, v[10:11]
	v_mov_b32_e32 v19, v20
	s_ashr_i32 s7, s6, 31
	v_lshl_add_u64 v[110:111], v[10:11], 0, s[22:23]
	v_add_u32_e32 v10, v13, v8
	v_lshl_add_u64 v[18:19], s[6:7], 1, v[18:19]
	s_waitcnt vmcnt(1)
	ds_write_b128 v10, v[78:81]
	v_add_u32_e32 v4, v15, v8
	v_bfe_u32 v114, v115, 5, 1
	v_lshl_add_u64 v[18:19], v[18:19], 0, s[22:23]
	s_waitcnt vmcnt(0)
	ds_write_b128 v4, v[82:85]
	v_lshlrev_b32_e32 v0, 4, v114
	v_mov_b32_e32 v1, v129
	v_lshl_add_u64 v[0:1], v[18:19], 0, v[0:1]
	global_load_dwordx4 v[64:67], v[0:1], off
	global_load_dwordx4 v[104:107], v[0:1], off offset:32
	global_load_dwordx4 v[100:103], v[0:1], off offset:64
	global_load_dwordx4 v[96:99], v[0:1], off offset:96
	global_load_dwordx4 v[92:95], v[0:1], off offset:128
	global_load_dwordx4 v[88:91], v[0:1], off offset:160
	global_load_dwordx4 v[84:87], v[0:1], off offset:192
	global_load_dwordx4 v[80:83], v[0:1], off offset:224
	v_lshlrev_b32_e32 v0, 8, v115
	v_lshrrev_b32_e32 v9, 5, v115
	v_readfirstlane_b32 s4, v115
	v_and_b32_e32 v0, 0x1f00, v0
	s_bfe_u32 s4, s4, 0x20006
	v_add_u32_e32 v68, 0, v0
	v_bitop3_b32 v0, v9, v16, 1 bitop3:0x6c
	v_lshlrev_b32_e32 v69, 4, v0
	v_lshl_add_u32 v17, s4, 13, v68
	v_add_u32_e32 v0, v17, v69
	s_waitcnt lgkmcnt(0)
	s_barrier
	ds_read_b128 v[0:3], v0
	v_bitop3_b32 v18, v114, v16, 2 bitop3:0x36
	v_lshlrev_b32_e32 v122, 4, v18
	v_add_u32_e32 v18, v17, v122
	ds_read_b128 v[18:21], v18
	s_add_i32 s7, s4, 3
	v_lshl_add_u32 v74, s7, 13, v68
	v_add_u32_e32 v70, v74, v122
	s_add_i32 s5, s4, 1
	s_add_i32 s6, s4, 2
	s_or_b32 s8, s4, 4
	v_lshl_add_u32 v36, s5, 13, v68
	v_lshl_add_u32 v52, s6, 13, v68
	v_lshl_add_u32 v126, s8, 13, v68
	v_add_u32_e32 v32, v36, v122
	v_add_u32_e32 v48, v52, v122
	v_add_u32_e32 v122, v126, v122
	v_add_u32_e32 v68, v126, v69
	v_lshlrev_b32_e32 v112, 3, v114
	v_mov_b32_e32 v113, v129
	s_waitcnt vmcnt(7) lgkmcnt(1)
	v_mfma_f32_32x32x16_bf16 v[0:15], v[0:3], v[64:67], 0
	ds_read_b128 v[70:73], v70
	ds_read_b128 v[122:125], v122
	ds_read_b128 v[32:35], v32
	ds_read_b128 v[48:51], v48
	s_waitcnt vmcnt(6) lgkmcnt(4)
	v_mfma_f32_32x32x16_bf16 v[0:15], v[18:21], v[104:107], v[0:15]
	v_bitop3_b32 v18, v114, v16, 4 bitop3:0x36
	v_lshlrev_b32_e32 v121, 4, v18
	v_add_u32_e32 v18, v17, v121
	ds_read_b128 v[18:21], v18
	s_waitcnt vmcnt(5) lgkmcnt(0)
	v_mfma_f32_32x32x16_bf16 v[0:15], v[18:21], v[100:103], v[0:15]
	v_bitop3_b32 v18, v114, v16, 6 bitop3:0x36
	v_lshlrev_b32_e32 v120, 4, v18
	v_add_u32_e32 v18, v17, v120
	ds_read_b128 v[18:21], v18
	s_waitcnt vmcnt(4) lgkmcnt(0)
	v_mfma_f32_32x32x16_bf16 v[0:15], v[18:21], v[96:99], v[0:15]
	v_bitop3_b32 v18, v114, v16, 8 bitop3:0x36
	v_lshlrev_b32_e32 v119, 4, v18
	v_add_u32_e32 v18, v17, v119
	ds_read_b128 v[18:21], v18
	s_waitcnt vmcnt(3) lgkmcnt(0)
	v_mfma_f32_32x32x16_bf16 v[0:15], v[18:21], v[92:95], v[0:15]
	v_bitop3_b32 v18, v114, v16, 10 bitop3:0x36
	v_lshlrev_b32_e32 v118, 4, v18
	v_add_u32_e32 v18, v17, v118
	ds_read_b128 v[18:21], v18
	s_waitcnt vmcnt(2) lgkmcnt(0)
	v_mfma_f32_32x32x16_bf16 v[0:15], v[18:21], v[88:91], v[0:15]
	v_bitop3_b32 v18, v114, v16, 12 bitop3:0x36
	v_lshlrev_b32_e32 v117, 4, v18
	v_add_u32_e32 v18, v17, v117
	ds_read_b128 v[18:21], v18
	v_bitop3_b32 v16, v114, v16, 14 bitop3:0x36
	v_lshlrev_b32_e32 v116, 4, v16
	v_add_u32_e32 v16, v17, v116
	s_waitcnt vmcnt(1) lgkmcnt(0)
	v_mfma_f32_32x32x16_bf16 v[0:15], v[18:21], v[84:87], v[0:15]
	ds_read_b128 v[16:19], v16
	s_waitcnt vmcnt(0) lgkmcnt(0)
	v_mfma_f32_32x32x16_bf16 v[0:15], v[16:19], v[80:83], v[0:15]
	v_add_u32_e32 v254, v36, v69
	ds_read_b128 v[242:245], v254
	v_add_u32_e32 v255, v36, v121
	ds_read_b128 v[246:249], v255
	v_add_u32_e32 v254, v36, v120
	ds_read_b128 v[250:253], v254
	s_waitcnt lgkmcnt(2)
	v_mfma_f32_32x32x16_bf16 v[16:31], v[242:245], v[64:67], 0
	v_mfma_f32_32x32x16_bf16 v[16:31], v[32:35], v[104:107], v[16:31]
	v_add_u32_e32 v255, v36, v119
	ds_read_b128 v[242:245], v255
	s_waitcnt lgkmcnt(2)
	v_mfma_f32_32x32x16_bf16 v[16:31], v[246:249], v[100:103], v[16:31]
	v_add_u32_e32 v254, v36, v118
	ds_read_b128 v[246:249], v254
	s_waitcnt lgkmcnt(2)
	v_mfma_f32_32x32x16_bf16 v[16:31], v[250:253], v[96:99], v[16:31]
	v_add_u32_e32 v255, v36, v117
	ds_read_b128 v[250:253], v255
	s_waitcnt lgkmcnt(2)
	v_mfma_f32_32x32x16_bf16 v[16:31], v[242:245], v[92:95], v[16:31]
	v_add_u32_e32 v254, v36, v116
	ds_read_b128 v[242:245], v254
	s_waitcnt lgkmcnt(2)
	v_mfma_f32_32x32x16_bf16 v[16:31], v[246:249], v[88:91], v[16:31]
	v_add_u32_e32 v255, v52, v69
	ds_read_b128 v[246:249], v255
	s_waitcnt lgkmcnt(2)
	v_mfma_f32_32x32x16_bf16 v[16:31], v[250:253], v[84:87], v[16:31]
	v_add_u32_e32 v254, v52, v121
	ds_read_b128 v[250:253], v254
	s_waitcnt lgkmcnt(2)
	v_mfma_f32_32x32x16_bf16 v[16:31], v[242:245], v[80:83], v[16:31]
	v_add_u32_e32 v255, v52, v120
	ds_read_b128 v[242:245], v255
	s_waitcnt lgkmcnt(2)
	v_mfma_f32_32x32x16_bf16 v[32:47], v[246:249], v[64:67], 0
	v_mfma_f32_32x32x16_bf16 v[32:47], v[48:51], v[104:107], v[32:47]
	v_add_u32_e32 v254, v52, v119
	ds_read_b128 v[246:249], v254
	s_waitcnt lgkmcnt(2)
	v_mfma_f32_32x32x16_bf16 v[32:47], v[250:253], v[100:103], v[32:47]
	v_add_u32_e32 v255, v52, v118
	ds_read_b128 v[250:253], v255
	s_waitcnt lgkmcnt(2)
	v_mfma_f32_32x32x16_bf16 v[32:47], v[242:245], v[96:99], v[32:47]
	v_add_u32_e32 v254, v52, v117
	ds_read_b128 v[242:245], v254
	s_waitcnt lgkmcnt(2)
	v_mfma_f32_32x32x16_bf16 v[32:47], v[246:249], v[92:95], v[32:47]
	v_add_u32_e32 v255, v52, v116
	ds_read_b128 v[246:249], v255
	s_waitcnt lgkmcnt(2)
	v_mfma_f32_32x32x16_bf16 v[32:47], v[250:253], v[88:91], v[32:47]
	v_add_u32_e32 v254, v74, v69
	ds_read_b128 v[250:253], v254
	s_waitcnt lgkmcnt(2)
	v_mfma_f32_32x32x16_bf16 v[32:47], v[242:245], v[84:87], v[32:47]
	v_add_u32_e32 v255, v74, v121
	ds_read_b128 v[242:245], v255
	s_waitcnt lgkmcnt(2)
	v_mfma_f32_32x32x16_bf16 v[32:47], v[246:249], v[80:83], v[32:47]
	v_add_u32_e32 v254, v74, v120
	ds_read_b128 v[246:249], v254
	s_waitcnt lgkmcnt(2)
	v_mfma_f32_32x32x16_bf16 v[48:63], v[250:253], v[64:67], 0
	v_mfma_f32_32x32x16_bf16 v[48:63], v[70:73], v[104:107], v[48:63]
	v_add_u32_e32 v255, v74, v119
	ds_read_b128 v[250:253], v255
	s_waitcnt lgkmcnt(2)
	v_mfma_f32_32x32x16_bf16 v[48:63], v[242:245], v[100:103], v[48:63]
	v_add_u32_e32 v254, v74, v118
	ds_read_b128 v[242:245], v254
	s_waitcnt lgkmcnt(2)
	v_mfma_f32_32x32x16_bf16 v[48:63], v[246:249], v[96:99], v[48:63]
	v_add_u32_e32 v255, v74, v117
	ds_read_b128 v[246:249], v255
	s_waitcnt lgkmcnt(2)
	v_mfma_f32_32x32x16_bf16 v[48:63], v[250:253], v[92:95], v[48:63]
	v_add_u32_e32 v254, v74, v116
	ds_read_b128 v[250:253], v254
	s_waitcnt lgkmcnt(2)
	v_mfma_f32_32x32x16_bf16 v[48:63], v[242:245], v[88:91], v[48:63]
	ds_read_b128 v[242:245], v68
	s_waitcnt lgkmcnt(2)
	v_mfma_f32_32x32x16_bf16 v[48:63], v[246:249], v[84:87], v[48:63]
	v_add_u32_e32 v254, v126, v121
	ds_read_b128 v[246:249], v254
	s_waitcnt lgkmcnt(2)
	v_mfma_f32_32x32x16_bf16 v[48:63], v[250:253], v[80:83], v[48:63]
	v_add_u32_e32 v255, v126, v120
	ds_read_b128 v[250:253], v255
	s_waitcnt lgkmcnt(2)
	v_mfma_f32_32x32x16_bf16 v[64:79], v[242:245], v[64:67], 0
	v_mfma_f32_32x32x16_bf16 v[64:79], v[122:125], v[104:107], v[64:79]
	s_waitcnt lgkmcnt(1)
	v_mfma_f32_32x32x16_bf16 v[64:79], v[246:249], v[100:103], v[64:79]
	s_waitcnt lgkmcnt(0)
	v_mfma_f32_32x32x16_bf16 v[64:79], v[250:253], v[96:99], v[64:79]
	v_add_u32_e32 v96, v126, v119
	ds_read_b128 v[96:99], v96
	v_lshlrev_b32_e32 v100, 2, v114
	v_lshl_or_b32 v107, s4, 5, v100
	v_max_u32_e32 v101, s11, v128
	v_cmp_le_u32_e32 vcc, v101, v107
	v_or_b32_e32 v103, 0x80, v128
	s_waitcnt lgkmcnt(0)
	v_mfma_f32_32x32x16_bf16 v[64:79], v[96:99], v[92:95], v[64:79]
	v_add_u32_e32 v92, v126, v118
	ds_read_b128 v[92:95], v92
	v_cndmask_b32_e32 v0, v218, v0, vcc
	v_lshl_or_b32 v106, s5, 5, v100
	v_cmp_le_u32_e64 s[38:39], v101, v106
	s_mov_b32 s4, 0xff800000
	v_lshl_or_b32 v105, s6, 5, v100
	s_waitcnt lgkmcnt(0)
	v_mfma_f32_32x32x16_bf16 v[64:79], v[92:95], v[88:91], v[64:79]
	v_add_u32_e32 v88, v126, v117
	ds_read_b128 v[88:91], v88
	v_lshl_or_b32 v102, s7, 5, v100
	s_waitcnt lgkmcnt(0)
	v_mfma_f32_32x32x16_bf16 v[64:79], v[88:91], v[84:87], v[64:79]
	v_add_u32_e32 v84, v126, v116
	ds_read_b128 v[84:87], v84
	s_waitcnt lgkmcnt(0)
	v_mfma_f32_32x32x16_bf16 v[64:79], v[84:87], v[80:83], v[64:79]
	v_or_b32_e32 v80, 1, v107
	v_cmp_le_u32_e32 vcc, v101, v80
	v_or_b32_e32 v81, 2, v107
	s_nop 0
	v_cndmask_b32_e32 v1, v218, v1, vcc
	v_cmp_le_u32_e32 vcc, v101, v81
	v_or_b32_e32 v81, 3, v107
	v_max3_f32 v80, v0, s4, v1
	v_cndmask_b32_e32 v2, v218, v2, vcc
	v_cmp_le_u32_e32 vcc, v101, v81
	v_or_b32_e32 v81, 8, v107
	s_movk_i32 s4, 0x80
	v_cndmask_b32_e32 v3, v218, v3, vcc
	v_cmp_le_u32_e32 vcc, v101, v81
	v_max3_f32 v80, v80, v2, v3
	s_nop 0
	v_cndmask_b32_e32 v104, v218, v4, vcc
	v_or_b32_e32 v4, 9, v107
	v_cmp_le_u32_e32 vcc, v101, v4
	s_nop 1
	v_cndmask_b32_e32 v116, v218, v5, vcc
	v_or_b32_e32 v5, 10, v107
	v_cmp_le_u32_e32 vcc, v101, v5
	v_or_b32_e32 v5, 11, v107
	v_max3_f32 v4, v80, v104, v116
	v_cndmask_b32_e32 v117, v218, v6, vcc
	v_cmp_le_u32_e32 vcc, v101, v5
	v_or_b32_e32 v5, 16, v107
	v_or_b32_e32 v6, 3, v105
	v_cndmask_b32_e32 v118, v218, v7, vcc
	v_cmp_le_u32_e32 vcc, v101, v5
	v_or_b32_e32 v5, 17, v107
	v_max3_f32 v4, v4, v117, v118
	v_cndmask_b32_e32 v98, v218, v8, vcc
	v_cmp_le_u32_e32 vcc, v101, v5
	v_or_b32_e32 v5, 18, v107
	s_nop 0
	v_cndmask_b32_e32 v99, v218, v9, vcc
	v_cmp_le_u32_e32 vcc, v101, v5
	v_or_b32_e32 v5, 19, v107
	v_max3_f32 v4, v4, v98, v99
	v_cndmask_b32_e32 v96, v218, v10, vcc
	v_cmp_le_u32_e32 vcc, v101, v5
	v_or_b32_e32 v5, 24, v107
	v_or_b32_e32 v9, 9, v105
	v_cndmask_b32_e32 v97, v218, v11, vcc
	v_cmp_le_u32_e32 vcc, v101, v5
	v_or_b32_e32 v5, 25, v107
	v_max3_f32 v4, v4, v96, v97
	v_cndmask_b32_e32 v94, v218, v12, vcc
	v_cmp_le_u32_e32 vcc, v101, v5
	v_or_b32_e32 v5, 26, v107
	v_or_b32_e32 v12, 11, v105
	v_cndmask_b32_e32 v95, v218, v13, vcc
	v_cmp_le_u32_e32 vcc, v101, v5
	v_or_b32_e32 v5, 27, v107
	v_max3_f32 v4, v4, v94, v95
	v_cndmask_b32_e32 v92, v218, v14, vcc
	v_cmp_le_u32_e32 vcc, v101, v5
	v_or_b32_e32 v5, 1, v106
	v_or_b32_e32 v13, 17, v105
	v_cndmask_b32_e32 v93, v218, v15, vcc
	v_cmp_le_u32_e32 vcc, v106, v103
	s_and_b64 vcc, s[38:39], vcc
	v_cmp_le_u32_e64 s[38:39], v101, v5
	v_cndmask_b32_e32 v88, v218, v16, vcc
	v_cmp_lt_u32_e32 vcc, v106, v103
	s_and_b64 vcc, s[38:39], vcc
	v_or_b32_e32 v5, 2, v106
	v_cndmask_b32_e32 v85, v218, v17, vcc
	v_cmp_le_u32_e32 vcc, v5, v103
	v_cmp_le_u32_e64 s[38:39], v101, v5
	s_and_b64 vcc, s[38:39], vcc
	v_or_b32_e32 v5, 3, v106
	v_cndmask_b32_e32 v89, v218, v18, vcc
	v_cmp_le_u32_e32 vcc, v5, v103
	v_cmp_le_u32_e64 s[38:39], v101, v5
	s_and_b64 vcc, s[38:39], vcc
	v_or_b32_e32 v5, 8, v106
	v_cndmask_b32_e32 v91, v218, v19, vcc
	v_cmp_le_u32_e32 vcc, v5, v103
	v_cmp_le_u32_e64 s[38:39], v101, v5
	s_and_b64 vcc, s[38:39], vcc
	v_or_b32_e32 v5, 9, v106
	v_cndmask_b32_e32 v86, v218, v20, vcc
	v_cmp_le_u32_e32 vcc, v5, v103
	v_cmp_le_u32_e64 s[38:39], v101, v5
	s_and_b64 vcc, s[38:39], vcc
	v_or_b32_e32 v5, 10, v106
	v_cndmask_b32_e32 v84, v218, v21, vcc
	v_cmp_le_u32_e32 vcc, v5, v103
	v_cmp_le_u32_e64 s[38:39], v101, v5
	s_and_b64 vcc, s[38:39], vcc
	v_or_b32_e32 v5, 11, v106
	v_cndmask_b32_e32 v87, v218, v22, vcc
	v_cmp_le_u32_e32 vcc, v5, v103
	v_cmp_le_u32_e64 s[38:39], v101, v5
	s_and_b64 vcc, s[38:39], vcc
	v_or_b32_e32 v5, 16, v106
	v_cndmask_b32_e32 v90, v218, v23, vcc
	v_cmp_le_u32_e32 vcc, v5, v103
	v_cmp_le_u32_e64 s[38:39], v101, v5
	s_and_b64 vcc, s[38:39], vcc
	v_or_b32_e32 v5, 17, v106
	v_cndmask_b32_e32 v81, v218, v24, vcc
	v_cmp_le_u32_e32 vcc, v5, v103
	v_cmp_le_u32_e64 s[38:39], v101, v5
	s_and_b64 vcc, s[38:39], vcc
	v_or_b32_e32 v5, 18, v106
	v_cndmask_b32_e32 v80, v218, v25, vcc
	v_cmp_le_u32_e32 vcc, v5, v103
	v_cmp_le_u32_e64 s[38:39], v101, v5
	s_and_b64 vcc, s[38:39], vcc
	v_or_b32_e32 v5, 19, v106
	v_cndmask_b32_e32 v82, v218, v26, vcc
	v_cmp_le_u32_e32 vcc, v5, v103
	v_cmp_le_u32_e64 s[38:39], v101, v5
	s_and_b64 vcc, s[38:39], vcc
	v_or_b32_e32 v5, 24, v106
	v_cndmask_b32_e32 v83, v218, v27, vcc
	v_cmp_le_u32_e32 vcc, v5, v103
	v_cmp_le_u32_e64 s[38:39], v101, v5
	v_max3_f32 v4, v4, v92, v93
	s_and_b64 vcc, s[38:39], vcc
	v_or_b32_e32 v5, 25, v106
	v_max3_f32 v4, v4, v88, v85
	v_cndmask_b32_e32 v28, v218, v28, vcc
	v_cmp_le_u32_e32 vcc, v5, v103
	v_cmp_le_u32_e64 s[38:39], v101, v5
	v_max3_f32 v4, v4, v89, v91
	s_and_b64 vcc, s[38:39], vcc
	v_or_b32_e32 v5, 26, v106
	v_max3_f32 v4, v4, v86, v84
	v_cndmask_b32_e32 v26, v218, v29, vcc
	v_cmp_le_u32_e32 vcc, v5, v103
	v_cmp_le_u32_e64 s[38:39], v101, v5
	v_max3_f32 v4, v4, v87, v90
	s_and_b64 vcc, s[38:39], vcc
	v_or_b32_e32 v5, 27, v106
	v_max3_f32 v4, v4, v81, v80
	v_cndmask_b32_e32 v25, v218, v30, vcc
	v_cmp_le_u32_e32 vcc, v5, v103
	v_cmp_le_u32_e64 s[38:39], v101, v5
	v_max3_f32 v4, v4, v82, v83
	s_and_b64 vcc, s[38:39], vcc
	v_max3_f32 v4, v4, v28, v26
	v_cndmask_b32_e32 v23, v218, v31, vcc
	v_cmp_le_u32_e32 vcc, v105, v103
	v_cmp_le_u32_e64 s[38:39], v101, v105
	v_max3_f32 v5, v4, v25, v23
	s_and_b64 vcc, s[38:39], vcc
	v_or_b32_e32 v4, 1, v105
	v_cndmask_b32_e32 v8, v218, v32, vcc
	v_cmp_lt_u32_e32 vcc, v105, v103
	v_cmp_le_u32_e64 s[38:39], v101, v4
	s_and_b64 vcc, s[38:39], vcc
	v_cndmask_b32_e32 v4, v218, v33, vcc
	v_max3_f32 v7, v5, v8, v4
	v_or_b32_e32 v5, 2, v105
	v_cmp_le_u32_e32 vcc, v5, v103
	v_cmp_le_u32_e64 s[38:39], v101, v5
	s_and_b64 vcc, s[38:39], vcc
	v_cndmask_b32_e32 v5, v218, v34, vcc
	v_cmp_le_u32_e32 vcc, v6, v103
	v_cmp_le_u32_e64 s[38:39], v101, v6
	s_and_b64 vcc, s[38:39], vcc
	v_cndmask_b32_e32 v6, v218, v35, vcc
	v_max3_f32 v10, v7, v5, v6
	v_or_b32_e32 v7, 8, v105
	v_cmp_le_u32_e32 vcc, v7, v103
	v_cmp_le_u32_e64 s[38:39], v101, v7
	s_and_b64 vcc, s[38:39], vcc
	v_cndmask_b32_e32 v7, v218, v36, vcc
	v_cmp_le_u32_e32 vcc, v9, v103
	v_cmp_le_u32_e64 s[38:39], v101, v9
	s_and_b64 vcc, s[38:39], vcc
	v_cndmask_b32_e32 v9, v218, v37, vcc
	v_max3_f32 v11, v10, v7, v9
	v_or_b32_e32 v10, 10, v105
	v_cmp_le_u32_e32 vcc, v10, v103
	v_cmp_le_u32_e64 s[38:39], v101, v10
	s_and_b64 vcc, s[38:39], vcc
	v_cndmask_b32_e32 v10, v218, v38, vcc
	v_cmp_le_u32_e32 vcc, v12, v103
	v_cmp_le_u32_e64 s[38:39], v101, v12
	s_and_b64 vcc, s[38:39], vcc
	v_cndmask_b32_e32 v12, v218, v39, vcc
	v_max3_f32 v14, v11, v10, v12
	v_or_b32_e32 v11, 16, v105
	v_cmp_le_u32_e32 vcc, v11, v103
	v_cmp_le_u32_e64 s[38:39], v101, v11
	s_and_b64 vcc, s[38:39], vcc
	v_cndmask_b32_e32 v11, v218, v40, vcc
	v_cmp_le_u32_e32 vcc, v13, v103
	v_cmp_le_u32_e64 s[38:39], v101, v13
	s_and_b64 vcc, s[38:39], vcc
	v_cndmask_b32_e32 v13, v218, v41, vcc
	v_max3_f32 v16, v14, v11, v13
	v_or_b32_e32 v14, 18, v105
	v_cmp_le_u32_e32 vcc, v14, v103
	v_cmp_le_u32_e64 s[38:39], v101, v14
	s_and_b64 vcc, s[38:39], vcc
	v_or_b32_e32 v15, 19, v105
	v_cndmask_b32_e32 v14, v218, v42, vcc
	v_cmp_le_u32_e32 vcc, v15, v103
	v_cmp_le_u32_e64 s[38:39], v101, v15
	s_and_b64 vcc, s[38:39], vcc
	v_cndmask_b32_e32 v15, v218, v43, vcc
	v_max3_f32 v18, v16, v14, v15
	v_or_b32_e32 v16, 24, v105
	v_cmp_le_u32_e32 vcc, v16, v103
	v_cmp_le_u32_e64 s[38:39], v101, v16
	s_and_b64 vcc, s[38:39], vcc
	v_or_b32_e32 v17, 25, v105
	v_cndmask_b32_e32 v16, v218, v44, vcc
	v_cmp_le_u32_e32 vcc, v17, v103
	v_cmp_le_u32_e64 s[38:39], v101, v17
	s_and_b64 vcc, s[38:39], vcc
	v_cndmask_b32_e32 v17, v218, v45, vcc
	v_max3_f32 v19, v18, v16, v17
	v_or_b32_e32 v18, 26, v105
	v_cmp_le_u32_e32 vcc, v18, v103
	v_cmp_le_u32_e64 s[38:39], v101, v18
	s_and_b64 vcc, s[38:39], vcc
	v_or_b32_e32 v20, 27, v105
	v_cndmask_b32_e32 v18, v218, v46, vcc
	v_cmp_le_u32_e32 vcc, v20, v103
	v_cmp_le_u32_e64 s[38:39], v101, v20
	s_and_b64 vcc, s[38:39], vcc
	v_cndmask_b32_e32 v20, v218, v47, vcc
	v_cmp_le_u32_e32 vcc, v102, v103
	v_cmp_le_u32_e64 s[38:39], v101, v102
	s_and_b64 vcc, s[38:39], vcc
	v_or_b32_e32 v21, 1, v102
	v_max3_f32 v22, v19, v18, v20
	v_cndmask_b32_e32 v19, v218, v48, vcc
	v_cmp_lt_u32_e32 vcc, v102, v103
	v_cmp_le_u32_e64 s[38:39], v101, v21
	s_and_b64 vcc, s[38:39], vcc
	v_cndmask_b32_e32 v21, v218, v49, vcc
	v_max3_f32 v27, v22, v19, v21
	v_or_b32_e32 v22, 2, v102
	v_cmp_le_u32_e32 vcc, v22, v103
	v_cmp_le_u32_e64 s[38:39], v101, v22
	s_and_b64 vcc, s[38:39], vcc
	v_or_b32_e32 v24, 3, v102
	v_cndmask_b32_e32 v22, v218, v50, vcc
	v_cmp_le_u32_e32 vcc, v24, v103
	v_cmp_le_u32_e64 s[38:39], v101, v24
	s_and_b64 vcc, s[38:39], vcc
	v_cndmask_b32_e32 v24, v218, v51, vcc
	v_max3_f32 v30, v27, v22, v24
	v_or_b32_e32 v27, 8, v102
	v_cmp_le_u32_e32 vcc, v27, v103
	v_cmp_le_u32_e64 s[38:39], v101, v27
	s_and_b64 vcc, s[38:39], vcc
	v_or_b32_e32 v29, 9, v102
	v_cndmask_b32_e32 v27, v218, v52, vcc
	v_cmp_le_u32_e32 vcc, v29, v103
	v_cmp_le_u32_e64 s[38:39], v101, v29
	s_and_b64 vcc, s[38:39], vcc
	v_cndmask_b32_e32 v29, v218, v53, vcc
	v_max3_f32 v31, v30, v27, v29
	v_or_b32_e32 v30, 10, v102
	v_cmp_le_u32_e32 vcc, v30, v103
	v_cmp_le_u32_e64 s[38:39], v101, v30
	s_and_b64 vcc, s[38:39], vcc
	v_or_b32_e32 v32, 11, v102
	v_cndmask_b32_e32 v30, v218, v54, vcc
	v_cmp_le_u32_e32 vcc, v32, v103
	v_cmp_le_u32_e64 s[38:39], v101, v32
	s_and_b64 vcc, s[38:39], vcc
	v_cndmask_b32_e32 v32, v218, v55, vcc
	v_max3_f32 v34, v31, v30, v32
	v_or_b32_e32 v31, 16, v102
	v_cmp_le_u32_e32 vcc, v31, v103
	v_cmp_le_u32_e64 s[38:39], v101, v31
	s_and_b64 vcc, s[38:39], vcc
	v_or_b32_e32 v33, 17, v102
	v_cndmask_b32_e32 v31, v218, v56, vcc
	v_cmp_le_u32_e32 vcc, v33, v103
	v_cmp_le_u32_e64 s[38:39], v101, v33
	s_and_b64 vcc, s[38:39], vcc
	v_cndmask_b32_e32 v33, v218, v57, vcc
	v_max3_f32 v36, v34, v31, v33
	v_or_b32_e32 v34, 18, v102
	v_cmp_le_u32_e32 vcc, v34, v103
	v_cmp_le_u32_e64 s[38:39], v101, v34
	s_and_b64 vcc, s[38:39], vcc
	v_or_b32_e32 v35, 19, v102
	v_cndmask_b32_e32 v34, v218, v58, vcc
	v_cmp_le_u32_e32 vcc, v35, v103
	v_cmp_le_u32_e64 s[38:39], v101, v35
	s_and_b64 vcc, s[38:39], vcc
	v_cndmask_b32_e32 v35, v218, v59, vcc
	v_max3_f32 v38, v36, v34, v35
	v_or_b32_e32 v36, 24, v102
	v_cmp_le_u32_e32 vcc, v36, v103
	v_cmp_le_u32_e64 s[38:39], v101, v36
	s_and_b64 vcc, s[38:39], vcc
	v_or_b32_e32 v37, 25, v102
	v_cndmask_b32_e32 v36, v218, v60, vcc
	v_cmp_le_u32_e32 vcc, v37, v103
	v_cmp_le_u32_e64 s[38:39], v101, v37
	s_and_b64 vcc, s[38:39], vcc
	v_cndmask_b32_e32 v37, v218, v61, vcc
	v_max3_f32 v39, v38, v36, v37
	v_or_b32_e32 v38, 26, v102
	v_cmp_le_u32_e32 vcc, v38, v103
	v_cmp_le_u32_e64 s[38:39], v101, v38
	s_and_b64 vcc, s[38:39], vcc
	v_or_b32_e32 v40, 27, v102
	v_cndmask_b32_e32 v38, v218, v62, vcc
	v_cmp_le_u32_e32 vcc, v40, v103
	v_cmp_le_u32_e64 s[38:39], v101, v40
	s_and_b64 vcc, s[38:39], vcc
	v_lshl_or_b32 v101, s8, 5, v100
	v_cndmask_b32_e32 v47, v218, v63, vcc
	v_cmp_le_u32_e32 vcc, v101, v103
	v_max3_f32 v40, v39, v38, v47
	v_or_b32_e32 v46, 19, v101
	v_cndmask_b32_e32 v41, v218, v64, vcc
	v_cmp_lt_u32_e32 vcc, v101, v103
	v_or_b32_e32 v51, 25, v101
	v_or_b32_e32 v55, 27, v101
	v_cndmask_b32_e32 v39, v218, v65, vcc
	v_cndmask_b32_e32 v42, v41, v64, vcc
	v_max3_f32 v40, v40, v41, v39
	v_or_b32_e32 v41, 2, v101
	v_cmp_le_u32_e32 vcc, v41, v103
	v_or_b32_e32 v41, 3, v101
	v_and_b32_e32 v58, 64, v214
	v_cndmask_b32_e32 v43, v218, v66, vcc
	v_cmp_le_u32_e32 vcc, v41, v103
	v_or_b32_e32 v41, 8, v101
	v_add_u32_e32 v58, 64, v58
	v_cndmask_b32_e32 v44, v218, v67, vcc
	v_cmp_le_u32_e32 vcc, v41, v103
	v_or_b32_e32 v41, 9, v101
	v_max3_f32 v40, v40, v43, v44
	v_cndmask_b32_e32 v48, v218, v68, vcc
	v_cmp_le_u32_e32 vcc, v41, v103
	v_or_b32_e32 v41, 10, v101
	s_nop 0
	v_cndmask_b32_e32 v49, v218, v69, vcc
	v_cmp_le_u32_e32 vcc, v41, v103
	v_or_b32_e32 v41, 11, v101
	v_max3_f32 v40, v40, v48, v49
	v_cndmask_b32_e32 v52, v218, v70, vcc
	v_cmp_le_u32_e32 vcc, v41, v103
	v_or_b32_e32 v41, 17, v101
	s_nop 0
	v_cndmask_b32_e32 v53, v218, v71, vcc
	v_max3_f32 v45, v40, v52, v53
	v_or_b32_e32 v40, 16, v101
	v_cmp_le_u32_e32 vcc, v40, v103
	s_nop 1
	v_cndmask_b32_e32 v40, v218, v72, vcc
	v_cmp_le_u32_e32 vcc, v41, v103
	s_nop 1
	v_cndmask_b32_e32 v41, v218, v73, vcc
	v_max3_f32 v50, v45, v40, v41
	v_or_b32_e32 v45, 18, v101
	v_cmp_le_u32_e32 vcc, v45, v103
	s_nop 1
	v_cndmask_b32_e32 v45, v218, v74, vcc
	v_cmp_le_u32_e32 vcc, v46, v103
	s_nop 1
	v_cndmask_b32_e32 v46, v218, v75, vcc
	v_max3_f32 v54, v50, v45, v46
	v_or_b32_e32 v50, 24, v101
	v_cmp_le_u32_e32 vcc, v50, v103
	s_nop 1
	v_cndmask_b32_e32 v50, v218, v76, vcc
	v_cmp_le_u32_e32 vcc, v51, v103
	s_nop 1
	v_cndmask_b32_e32 v51, v218, v77, vcc
	v_max3_f32 v56, v54, v50, v51
	v_or_b32_e32 v54, 26, v101
	v_cmp_le_u32_e32 vcc, v54, v103
	s_nop 1
	v_cndmask_b32_e32 v54, v218, v78, vcc
	v_cmp_le_u32_e32 vcc, v55, v103
	s_nop 1
	v_cndmask_b32_e32 v55, v218, v79, vcc
	v_max3_f32 v57, v56, v54, v55
	v_xor_b32_e32 v56, 32, v214
	v_cmp_lt_i32_e32 vcc, v56, v58
	s_nop 1
	v_cndmask_b32_e32 v56, v214, v56, vcc
	v_lshlrev_b32_e32 v56, 2, v56
	ds_bpermute_b32 v58, v56, v57
	s_waitcnt lgkmcnt(0)
	v_max_f32_e32 v58, v58, v58
	v_max_f32_e32 v100, v57, v58
	v_sub_f32_e32 v0, v0, v100
	v_exp_f32_e32 v0, v0
	v_sub_f32_e32 v1, v1, v100
	v_exp_f32_e32 v1, v1
	v_sub_f32_e32 v2, v2, v100
	v_exp_f32_e32 v2, v2
	v_sub_f32_e32 v3, v3, v100
	v_exp_f32_e32 v3, v3
	v_sub_f32_e32 v58, v104, v100
	v_sub_f32_e32 v59, v116, v100
	v_add_f32_e32 v57, 0, v0
	v_exp_f32_e32 v58, v58
	v_exp_f32_e32 v59, v59
	v_add_f32_e32 v57, v1, v57
	v_sub_f32_e32 v60, v117, v100
	v_sub_f32_e32 v61, v118, v100
	v_add_f32_e32 v57, v2, v57
	v_exp_f32_e32 v60, v60
	v_exp_f32_e32 v61, v61
	v_add_f32_e32 v57, v3, v57
	v_add_f32_e32 v57, v58, v57
	v_cvt_pk_bf16_f32 v0, v0, v1
	v_cvt_pk_bf16_f32 v1, v2, v3
	v_cvt_pk_bf16_f32 v2, v58, v59
	v_sub_f32_e32 v58, v98, v100
	v_add_f32_e32 v57, v59, v57
	v_exp_f32_e32 v58, v58
	v_sub_f32_e32 v59, v99, v100
	v_add_f32_e32 v57, v60, v57
	v_cvt_pk_bf16_f32 v3, v60, v61
	v_exp_f32_e32 v59, v59
	v_sub_f32_e32 v60, v96, v100
	v_add_f32_e32 v57, v61, v57
	v_exp_f32_e32 v60, v60
	v_sub_f32_e32 v61, v97, v100
	v_exp_f32_e32 v61, v61
	v_sub_f32_e32 v62, v94, v100
	v_add_f32_e32 v57, v58, v57
	v_exp_f32_e32 v62, v62
	v_sub_f32_e32 v63, v95, v100
	v_add_f32_e32 v57, v59, v57
	v_exp_f32_e32 v63, v63
	v_sub_f32_e32 v64, v92, v100
	v_add_f32_e32 v57, v60, v57
	v_exp_f32_e32 v64, v64
	v_sub_f32_e32 v65, v93, v100
	v_add_f32_e32 v57, v61, v57
	v_exp_f32_e32 v65, v65
	v_cvt_pk_bf16_f32 v96, v58, v59
	v_sub_f32_e32 v58, v88, v100
	v_add_f32_e32 v57, v62, v57
	v_exp_f32_e32 v58, v58
	v_sub_f32_e32 v59, v85, v100
	v_add_f32_e32 v57, v63, v57
	v_cvt_pk_bf16_f32 v97, v60, v61
	v_exp_f32_e32 v59, v59
	v_sub_f32_e32 v60, v89, v100
	v_add_f32_e32 v57, v64, v57
	v_exp_f32_e32 v60, v60
	v_sub_f32_e32 v61, v91, v100
	v_add_f32_e32 v57, v65, v57
	v_cvt_pk_bf16_f32 v98, v62, v63
	v_exp_f32_e32 v61, v61
	v_sub_f32_e32 v62, v86, v100
	v_add_f32_e32 v57, v58, v57
	v_exp_f32_e32 v62, v62
	v_sub_f32_e32 v63, v84, v100
	v_cvt_pk_bf16_f32 v99, v64, v65
	v_add_f32_e32 v57, v59, v57
	v_exp_f32_e32 v63, v63
	v_sub_f32_e32 v64, v87, v100
	v_add_f32_e32 v57, v60, v57
	v_exp_f32_e32 v64, v64
	v_sub_f32_e32 v65, v90, v100
	v_add_f32_e32 v57, v61, v57
	v_exp_f32_e32 v65, v65
	v_cvt_pk_bf16_f32 v92, v58, v59
	v_sub_f32_e32 v58, v81, v100
	v_add_f32_e32 v57, v62, v57
	v_exp_f32_e32 v58, v58
	v_sub_f32_e32 v59, v80, v100
	v_add_f32_e32 v57, v63, v57
	v_cvt_pk_bf16_f32 v93, v60, v61
	v_exp_f32_e32 v59, v59
	v_sub_f32_e32 v60, v82, v100
	v_add_f32_e32 v57, v64, v57
	v_exp_f32_e32 v60, v60
	v_sub_f32_e32 v61, v83, v100
	v_add_f32_e32 v57, v65, v57
	v_exp_f32_e32 v61, v61
	v_sub_f32_e32 v28, v28, v100
	v_add_f32_e32 v57, v58, v57
	v_exp_f32_e32 v28, v28
	v_sub_f32_e32 v26, v26, v100
	v_add_f32_e32 v57, v59, v57
	v_exp_f32_e32 v26, v26
	v_sub_f32_e32 v25, v25, v100
	v_add_f32_e32 v57, v60, v57
	v_exp_f32_e32 v25, v25
	v_sub_f32_e32 v23, v23, v100
	v_add_f32_e32 v57, v61, v57
	v_exp_f32_e32 v23, v23
	v_sub_f32_e32 v8, v8, v100
	v_add_f32_e32 v57, v28, v57
	v_exp_f32_e32 v8, v8
	v_sub_f32_e32 v4, v4, v100
	v_add_f32_e32 v57, v26, v57
	v_exp_f32_e32 v4, v4
	v_sub_f32_e32 v5, v5, v100
	v_add_f32_e32 v57, v25, v57
	v_exp_f32_e32 v5, v5
	v_sub_f32_e32 v6, v6, v100
	v_add_f32_e32 v57, v23, v57
	v_exp_f32_e32 v6, v6
	v_sub_f32_e32 v7, v7, v100
	v_cvt_pk_bf16_f32 v91, v25, v23
	v_add_f32_e32 v23, v8, v57
	v_exp_f32_e32 v7, v7
	v_sub_f32_e32 v9, v9, v100
	v_add_f32_e32 v23, v4, v23
	v_exp_f32_e32 v9, v9
	v_sub_f32_e32 v10, v10, v100
	v_add_f32_e32 v23, v5, v23
	v_exp_f32_e32 v10, v10
	v_sub_f32_e32 v12, v12, v100
	v_add_f32_e32 v23, v6, v23
	v_exp_f32_e32 v12, v12
	v_cvt_pk_bf16_f32 v84, v8, v4
	v_sub_f32_e32 v4, v11, v100
	v_add_f32_e32 v23, v7, v23
	v_cvt_pk_bf16_f32 v85, v5, v6
	v_exp_f32_e32 v4, v4
	v_sub_f32_e32 v6, v13, v100
	v_add_f32_e32 v23, v9, v23
	v_cvt_pk_bf16_f32 v86, v7, v9
	v_exp_f32_e32 v6, v6
	v_sub_f32_e32 v7, v14, v100
	v_add_f32_e32 v23, v10, v23
	v_exp_f32_e32 v7, v7
	v_sub_f32_e32 v8, v15, v100
	v_add_f32_e32 v23, v12, v23
	v_exp_f32_e32 v8, v8
	v_sub_f32_e32 v9, v16, v100
	v_cvt_pk_bf16_f32 v87, v10, v12
	v_add_f32_e32 v5, v4, v23
	v_exp_f32_e32 v9, v9
	v_sub_f32_e32 v10, v17, v100
	v_add_f32_e32 v5, v6, v5
	v_exp_f32_e32 v10, v10
	v_sub_f32_e32 v11, v18, v100
	v_add_f32_e32 v5, v7, v5
	v_exp_f32_e32 v11, v11
	v_sub_f32_e32 v12, v20, v100
	v_add_f32_e32 v5, v8, v5
	v_exp_f32_e32 v12, v12
	v_cvt_pk_bf16_f32 v80, v4, v6
	v_sub_f32_e32 v4, v19, v100
	v_add_f32_e32 v5, v9, v5
	v_exp_f32_e32 v4, v4
	v_sub_f32_e32 v6, v21, v100
	v_add_f32_e32 v5, v10, v5
	v_cvt_pk_bf16_f32 v81, v7, v8
	v_exp_f32_e32 v6, v6
	v_sub_f32_e32 v7, v22, v100
	v_add_f32_e32 v5, v11, v5
	v_exp_f32_e32 v7, v7
	v_sub_f32_e32 v8, v24, v100
	v_add_f32_e32 v5, v12, v5
	v_cvt_pk_bf16_f32 v82, v9, v10
	v_exp_f32_e32 v8, v8
	v_sub_f32_e32 v9, v27, v100
	v_add_f32_e32 v5, v4, v5
	v_exp_f32_e32 v9, v9
	v_sub_f32_e32 v10, v29, v100
	v_cvt_pk_bf16_f32 v83, v11, v12
	v_add_f32_e32 v5, v6, v5
	v_exp_f32_e32 v10, v10
	v_sub_f32_e32 v11, v30, v100
	v_add_f32_e32 v5, v7, v5
	v_exp_f32_e32 v11, v11
	v_sub_f32_e32 v12, v32, v100
	v_add_f32_e32 v5, v8, v5
	v_exp_f32_e32 v12, v12
	v_cvt_pk_bf16_f32 v76, v4, v6
	v_sub_f32_e32 v4, v31, v100
	v_add_f32_e32 v5, v9, v5
	v_exp_f32_e32 v4, v4
	v_sub_f32_e32 v6, v33, v100
	v_add_f32_e32 v5, v10, v5
	v_cvt_pk_bf16_f32 v77, v7, v8
	v_exp_f32_e32 v6, v6
	v_sub_f32_e32 v7, v34, v100
	v_add_f32_e32 v5, v11, v5
	v_exp_f32_e32 v7, v7
	v_sub_f32_e32 v8, v35, v100
	v_add_f32_e32 v5, v12, v5
	v_cvt_pk_bf16_f32 v78, v9, v10
	v_exp_f32_e32 v8, v8
	v_sub_f32_e32 v9, v36, v100
	v_add_f32_e32 v5, v4, v5
	v_exp_f32_e32 v9, v9
	v_sub_f32_e32 v10, v37, v100
	v_cvt_pk_bf16_f32 v79, v11, v12
	v_add_f32_e32 v5, v6, v5
	v_exp_f32_e32 v10, v10
	v_sub_f32_e32 v11, v38, v100
	v_add_f32_e32 v5, v7, v5
	v_exp_f32_e32 v11, v11
	v_sub_f32_e32 v12, v47, v100
	v_add_f32_e32 v5, v8, v5
	v_exp_f32_e32 v12, v12
	v_cvt_pk_bf16_f32 v72, v4, v6
	v_sub_f32_e32 v4, v42, v100
	v_add_f32_e32 v5, v9, v5
	v_exp_f32_e32 v4, v4
	v_sub_f32_e32 v6, v39, v100
	v_add_f32_e32 v5, v10, v5
	v_cvt_pk_bf16_f32 v73, v7, v8
	v_exp_f32_e32 v6, v6
	v_sub_f32_e32 v7, v43, v100
	v_add_f32_e32 v5, v11, v5
	v_exp_f32_e32 v7, v7
	v_sub_f32_e32 v8, v44, v100
	v_add_f32_e32 v5, v12, v5
	v_cvt_pk_bf16_f32 v74, v9, v10
	v_exp_f32_e32 v8, v8
	v_sub_f32_e32 v9, v48, v100
	v_add_f32_e32 v5, v4, v5
	v_exp_f32_e32 v9, v9
	v_sub_f32_e32 v10, v49, v100
	v_cvt_pk_bf16_f32 v75, v11, v12
	v_add_f32_e32 v5, v6, v5
	v_exp_f32_e32 v10, v10
	v_sub_f32_e32 v11, v52, v100
	v_add_f32_e32 v5, v7, v5
	v_exp_f32_e32 v11, v11
	v_sub_f32_e32 v12, v53, v100
	v_add_f32_e32 v5, v8, v5
	v_exp_f32_e32 v12, v12
	v_cvt_pk_bf16_f32 v68, v4, v6
	v_sub_f32_e32 v4, v40, v100
	v_add_f32_e32 v5, v9, v5
	v_exp_f32_e32 v4, v4
	v_sub_f32_e32 v6, v41, v100
	v_add_f32_e32 v5, v10, v5
	v_cvt_pk_bf16_f32 v69, v7, v8
	v_exp_f32_e32 v6, v6
	v_sub_f32_e32 v7, v45, v100
	v_add_f32_e32 v5, v11, v5
	v_exp_f32_e32 v7, v7
	v_sub_f32_e32 v8, v46, v100
	v_add_f32_e32 v5, v12, v5
	v_cvt_pk_bf16_f32 v70, v9, v10
	v_exp_f32_e32 v8, v8
	v_sub_f32_e32 v9, v50, v100
	v_sub_f32_e32 v10, v51, v100
	v_add_f32_e32 v5, v4, v5
	v_exp_f32_e32 v9, v9
	v_exp_f32_e32 v10, v10
	v_add_f32_e32 v5, v6, v5
	v_add_f32_e32 v5, v7, v5
	v_cvt_pk_bf16_f32 v95, v64, v65
	v_cvt_pk_bf16_f32 v71, v11, v12
	v_add_f32_e32 v5, v8, v5
	v_sub_f32_e32 v11, v54, v100
	v_cvt_pk_bf16_f32 v64, v4, v6
	v_lshlrev_b32_e32 v4, 1, v115
	v_add_f32_e32 v5, v9, v5
	v_exp_f32_e32 v11, v11
	v_sub_f32_e32 v12, v55, v100
	v_cvt_pk_bf16_f32 v66, v9, v10
	v_and_b32_e32 v9, 32, v4
	v_lshlrev_b32_e32 v4, 3, v115
	v_exp_f32_e32 v12, v12
	v_bfe_u32 v116, v115, 2, 2
	v_and_b32_e32 v4, 24, v4
	v_cvt_pk_bf16_f32 v65, v7, v8
	v_lshlrev_b32_e32 v8, 6, v116
	v_add_u32_e32 v115, s10, v4
	v_or_b32_e32 v4, v107, v116
	v_add_f32_e32 v5, v10, v5
	v_or_b32_e32 v118, v8, v9
	v_lshl_add_u32 v10, v4, 8, v115
	v_add_f32_e32 v5, v11, v5
	v_add_u32_e32 v122, v10, v118
	v_add_f32_e32 v103, v12, v5
	ds_read_b64_tr_b16 v[4:5], v122
	ds_read_b64_tr_b16 v[6:7], v122 offset:2048
	v_bitop3_b32 v107, v9, v8, 64 bitop3:0x36
	v_add_u32_e32 v124, v10, v107
	v_cvt_pk_bf16_f32 v94, v62, v63
	v_cvt_pk_bf16_f32 v88, v58, v59
	v_cvt_pk_bf16_f32 v89, v60, v61
	ds_bpermute_b32 v104, v56, v103
	s_waitcnt lgkmcnt(1)
	v_mfma_f32_32x32x16_bf16 v[48:63], v[4:7], v[0:3], 0
	ds_read_b64_tr_b16 v[4:5], v124
	ds_read_b64_tr_b16 v[6:7], v124 offset:2048
	v_bitop3_b32 v117, v9, v8, s4 bitop3:0x36
	v_add_u32_e32 v125, v10, v117
	s_movk_i32 s4, 0xc0
	v_bitop3_b32 v119, v9, v8, s4 bitop3:0x36
	v_add_u32_e32 v126, v10, v119
	v_cvt_pk_bf16_f32 v90, v28, v26
	s_waitcnt lgkmcnt(0)
	v_mfma_f32_32x32x16_bf16 v[32:47], v[4:7], v[0:3], 0
	ds_read_b64_tr_b16 v[4:5], v125
	ds_read_b64_tr_b16 v[6:7], v125 offset:2048
	v_cvt_pk_bf16_f32 v67, v11, v12
	s_waitcnt lgkmcnt(0)
	v_mfma_f32_32x32x16_bf16 v[16:31], v[4:7], v[0:3], 0
	ds_read_b64_tr_b16 v[4:5], v126
	ds_read_b64_tr_b16 v[6:7], v126 offset:2048
	ds_read_b64_tr_b16 v[120:121], v122 offset:4096
	ds_read_b64_tr_b16 v[122:123], v122 offset:6144
	s_waitcnt lgkmcnt(0)
	v_mfma_f32_32x32x16_bf16 v[48:63], v[120:123], v[96:99], v[48:63]
	ds_read_b64_tr_b16 v[120:121], v124 offset:4096
	ds_read_b64_tr_b16 v[122:123], v124 offset:6144
	s_waitcnt lgkmcnt(0)
	v_mfma_f32_32x32x16_bf16 v[32:47], v[120:123], v[96:99], v[32:47]
	ds_read_b64_tr_b16 v[120:121], v125 offset:4096
	ds_read_b64_tr_b16 v[122:123], v125 offset:6144
	v_mfma_f32_32x32x16_bf16 v[0:15], v[4:7], v[0:3], 0
	s_waitcnt lgkmcnt(0)
	v_mfma_f32_32x32x16_bf16 v[16:31], v[120:123], v[96:99], v[16:31]
	ds_read_b64_tr_b16 v[120:121], v126 offset:4096
	ds_read_b64_tr_b16 v[122:123], v126 offset:6144
	s_waitcnt lgkmcnt(0)
	v_mfma_f32_32x32x16_bf16 v[0:15], v[120:123], v[96:99], v[0:15]
	v_or_b32_e32 v96, v106, v116
	v_lshl_add_u32 v106, v96, 8, v115
	v_add_u32_e32 v120, v106, v118
	ds_read_b64_tr_b16 v[96:97], v120
	ds_read_b64_tr_b16 v[98:99], v120 offset:2048
	v_add_u32_e32 v121, v106, v107
	v_add_u32_e32 v122, v106, v117
	v_add_u32_e32 v106, v106, v119
	s_waitcnt lgkmcnt(0)
	v_mfma_f32_32x32x16_bf16 v[48:63], v[96:99], v[92:95], v[48:63]
	ds_read_b64_tr_b16 v[96:97], v121
	ds_read_b64_tr_b16 v[98:99], v121 offset:2048
	s_waitcnt lgkmcnt(0)
	v_mfma_f32_32x32x16_bf16 v[32:47], v[96:99], v[92:95], v[32:47]
	ds_read_b64_tr_b16 v[96:97], v122
	ds_read_b64_tr_b16 v[98:99], v122 offset:2048
	s_waitcnt lgkmcnt(0)
	v_mfma_f32_32x32x16_bf16 v[16:31], v[96:99], v[92:95], v[16:31]
	ds_read_b64_tr_b16 v[96:97], v106
	ds_read_b64_tr_b16 v[98:99], v106 offset:2048
	s_waitcnt lgkmcnt(0)
	v_mfma_f32_32x32x16_bf16 v[0:15], v[96:99], v[92:95], v[0:15]
	ds_read_b64_tr_b16 v[92:93], v120 offset:4096
	ds_read_b64_tr_b16 v[94:95], v120 offset:6144
	s_waitcnt lgkmcnt(0)
	v_mfma_f32_32x32x16_bf16 v[48:63], v[92:95], v[88:91], v[48:63]
	ds_read_b64_tr_b16 v[92:93], v121 offset:4096
	ds_read_b64_tr_b16 v[94:95], v121 offset:6144
	s_waitcnt lgkmcnt(0)
	v_mfma_f32_32x32x16_bf16 v[32:47], v[92:95], v[88:91], v[32:47]
	ds_read_b64_tr_b16 v[92:93], v122 offset:4096
	ds_read_b64_tr_b16 v[94:95], v122 offset:6144
	s_waitcnt lgkmcnt(0)
	v_mfma_f32_32x32x16_bf16 v[16:31], v[92:95], v[88:91], v[16:31]
	ds_read_b64_tr_b16 v[92:93], v106 offset:4096
	ds_read_b64_tr_b16 v[94:95], v106 offset:6144
	s_waitcnt lgkmcnt(0)
	v_mfma_f32_32x32x16_bf16 v[0:15], v[92:95], v[88:91], v[0:15]
	v_or_b32_e32 v88, v105, v116
	v_lshl_add_u32 v92, v88, 8, v115
	v_add_u32_e32 v93, v92, v118
	ds_read_b64_tr_b16 v[88:89], v93
	ds_read_b64_tr_b16 v[90:91], v93 offset:2048
	v_add_u32_e32 v94, v92, v107
	v_add_u32_e32 v95, v92, v117
	v_add_u32_e32 v92, v92, v119
	s_waitcnt lgkmcnt(0)
	v_mfma_f32_32x32x16_bf16 v[48:63], v[88:91], v[84:87], v[48:63]
	ds_read_b64_tr_b16 v[88:89], v94
	ds_read_b64_tr_b16 v[90:91], v94 offset:2048
	s_waitcnt lgkmcnt(0)
	v_mfma_f32_32x32x16_bf16 v[32:47], v[88:91], v[84:87], v[32:47]
	ds_read_b64_tr_b16 v[88:89], v95
	ds_read_b64_tr_b16 v[90:91], v95 offset:2048
	s_waitcnt lgkmcnt(0)
	v_mfma_f32_32x32x16_bf16 v[16:31], v[88:91], v[84:87], v[16:31]
	ds_read_b64_tr_b16 v[88:89], v92
	ds_read_b64_tr_b16 v[90:91], v92 offset:2048
	s_waitcnt lgkmcnt(0)
	v_mfma_f32_32x32x16_bf16 v[0:15], v[88:91], v[84:87], v[0:15]
	ds_read_b64_tr_b16 v[84:85], v93 offset:4096
	ds_read_b64_tr_b16 v[86:87], v93 offset:6144
	s_waitcnt lgkmcnt(0)
	v_mfma_f32_32x32x16_bf16 v[48:63], v[84:87], v[80:83], v[48:63]
	ds_read_b64_tr_b16 v[84:85], v94 offset:4096
	ds_read_b64_tr_b16 v[86:87], v94 offset:6144
	s_waitcnt lgkmcnt(0)
	v_mfma_f32_32x32x16_bf16 v[32:47], v[84:87], v[80:83], v[32:47]
	ds_read_b64_tr_b16 v[84:85], v95 offset:4096
	ds_read_b64_tr_b16 v[86:87], v95 offset:6144
	s_waitcnt lgkmcnt(0)
	v_mfma_f32_32x32x16_bf16 v[16:31], v[84:87], v[80:83], v[16:31]
	ds_read_b64_tr_b16 v[84:85], v92 offset:4096
	ds_read_b64_tr_b16 v[86:87], v92 offset:6144
	s_waitcnt lgkmcnt(0)
	v_mfma_f32_32x32x16_bf16 v[0:15], v[84:87], v[80:83], v[0:15]
	v_or_b32_e32 v80, v102, v116
	v_lshl_add_u32 v84, v80, 8, v115
	v_add_u32_e32 v85, v84, v118
	ds_read_b64_tr_b16 v[80:81], v85
	ds_read_b64_tr_b16 v[82:83], v85 offset:2048
	v_add_u32_e32 v86, v84, v107
	v_add_u32_e32 v87, v84, v117
	v_add_u32_e32 v84, v84, v119
	s_waitcnt lgkmcnt(0)
	v_mfma_f32_32x32x16_bf16 v[48:63], v[80:83], v[76:79], v[48:63]
	ds_read_b64_tr_b16 v[80:81], v86
	ds_read_b64_tr_b16 v[82:83], v86 offset:2048
	s_waitcnt lgkmcnt(0)
	v_mfma_f32_32x32x16_bf16 v[32:47], v[80:83], v[76:79], v[32:47]
	ds_read_b64_tr_b16 v[80:81], v87
	ds_read_b64_tr_b16 v[82:83], v87 offset:2048
	s_waitcnt lgkmcnt(0)
	v_mfma_f32_32x32x16_bf16 v[16:31], v[80:83], v[76:79], v[16:31]
	ds_read_b64_tr_b16 v[80:81], v84
	ds_read_b64_tr_b16 v[82:83], v84 offset:2048
	s_waitcnt lgkmcnt(0)
	v_mfma_f32_32x32x16_bf16 v[0:15], v[80:83], v[76:79], v[0:15]
	ds_read_b64_tr_b16 v[76:77], v85 offset:4096
	ds_read_b64_tr_b16 v[78:79], v85 offset:6144
	s_waitcnt lgkmcnt(0)
	v_mfma_f32_32x32x16_bf16 v[48:63], v[76:79], v[72:75], v[48:63]
	ds_read_b64_tr_b16 v[76:77], v86 offset:4096
	ds_read_b64_tr_b16 v[78:79], v86 offset:6144
	s_waitcnt lgkmcnt(0)
	v_mfma_f32_32x32x16_bf16 v[32:47], v[76:79], v[72:75], v[32:47]
	ds_read_b64_tr_b16 v[76:77], v87 offset:4096
	ds_read_b64_tr_b16 v[78:79], v87 offset:6144
	s_waitcnt lgkmcnt(0)
	v_mfma_f32_32x32x16_bf16 v[16:31], v[76:79], v[72:75], v[16:31]
	ds_read_b64_tr_b16 v[76:77], v84 offset:4096
	ds_read_b64_tr_b16 v[78:79], v84 offset:6144
	s_waitcnt lgkmcnt(0)
	v_mfma_f32_32x32x16_bf16 v[0:15], v[76:79], v[72:75], v[0:15]
	v_or_b32_e32 v72, v101, v116
	v_lshl_add_u32 v76, v72, 8, v115
	v_add_u32_e32 v77, v76, v118
	ds_read_b64_tr_b16 v[72:73], v77
	ds_read_b64_tr_b16 v[74:75], v77 offset:2048
	v_add_u32_e32 v78, v76, v107
	v_add_u32_e32 v79, v76, v117
	v_add_u32_e32 v76, v76, v119
	s_waitcnt lgkmcnt(0)
	v_mfma_f32_32x32x16_bf16 v[48:63], v[72:75], v[68:71], v[48:63]
	ds_read_b64_tr_b16 v[72:73], v78
	ds_read_b64_tr_b16 v[74:75], v78 offset:2048
	s_waitcnt lgkmcnt(0)
	v_mfma_f32_32x32x16_bf16 v[32:47], v[72:75], v[68:71], v[32:47]
	ds_read_b64_tr_b16 v[72:73], v79
	ds_read_b64_tr_b16 v[74:75], v79 offset:2048
	s_waitcnt lgkmcnt(0)
	v_mfma_f32_32x32x16_bf16 v[16:31], v[72:75], v[68:71], v[16:31]
	ds_read_b64_tr_b16 v[72:73], v76
	ds_read_b64_tr_b16 v[74:75], v76 offset:2048
	s_waitcnt lgkmcnt(0)
	v_mfma_f32_32x32x16_bf16 v[0:15], v[72:75], v[68:71], v[0:15]
	ds_read_b64_tr_b16 v[68:69], v77 offset:4096
	ds_read_b64_tr_b16 v[70:71], v77 offset:6144
	s_waitcnt lgkmcnt(0)
	v_mfma_f32_32x32x16_bf16 v[48:63], v[68:71], v[64:67], v[48:63]
	ds_read_b64_tr_b16 v[68:69], v78 offset:4096
	ds_read_b64_tr_b16 v[70:71], v78 offset:6144
	s_waitcnt lgkmcnt(0)
	v_mfma_f32_32x32x16_bf16 v[32:47], v[68:71], v[64:67], v[32:47]
	ds_read_b64_tr_b16 v[68:69], v79 offset:4096
	ds_read_b64_tr_b16 v[70:71], v79 offset:6144
	s_waitcnt lgkmcnt(0)
	v_mfma_f32_32x32x16_bf16 v[16:31], v[68:71], v[64:67], v[16:31]
	ds_read_b64_tr_b16 v[68:69], v76 offset:4096
	ds_read_b64_tr_b16 v[70:71], v76 offset:6144
	s_waitcnt lgkmcnt(0)
	v_mfma_f32_32x32x16_bf16 v[0:15], v[68:71], v[64:67], v[0:15]
	v_add_f32_e32 v64, v103, v104
	v_div_scale_f32 v65, s[4:5], v64, v64, 1.0
	v_rcp_f32_e32 v66, v65
	s_nop 0
	v_fma_f32 v67, -v65, v66, 1.0
	v_fmac_f32_e32 v66, v67, v66
	v_div_scale_f32 v67, vcc, 1.0, v64, 1.0
	v_mul_f32_e32 v68, v67, v66
	v_fma_f32 v69, -v65, v68, v67
	v_fmac_f32_e32 v68, v69, v66
	v_fma_f32 v65, -v65, v68, v67
	v_div_fmas_f32 v65, v65, v66, v68
	v_div_fixup_f32 v66, v65, v64, 1.0
	v_pk_mul_f32 v[48:49], v[48:49], v[66:67] op_sel_hi:[1,0]
	v_pk_mul_f32 v[50:51], v[50:51], v[66:67] op_sel_hi:[1,0]
	v_pk_mul_f32 v[32:33], v[32:33], v[66:67] op_sel_hi:[1,0]
	v_pk_mul_f32 v[34:35], v[34:35], v[66:67] op_sel_hi:[1,0]
	v_pk_mul_f32 v[16:17], v[66:67], v[16:17] op_sel_hi:[0,1]
	v_pk_mul_f32 v[18:19], v[66:67], v[18:19] op_sel_hi:[0,1]
	v_pk_mul_f32 v[0:1], v[66:67], v[0:1] op_sel_hi:[0,1]
	v_pk_mul_f32 v[2:3], v[66:67], v[2:3] op_sel_hi:[0,1]
	v_lshl_add_u64 v[68:69], v[110:111], 0, v[112:113]
	v_cvt_pk_bf16_f32 v48, v48, v49
	v_cvt_pk_bf16_f32 v49, v50, v51
	v_cvt_pk_bf16_f32 v32, v32, v33
	v_cvt_pk_bf16_f32 v33, v34, v35
	v_cvt_pk_bf16_f32 v16, v16, v17
	v_cvt_pk_bf16_f32 v17, v18, v19
	v_cvt_pk_bf16_f32 v0, v0, v1
	v_cvt_pk_bf16_f32 v1, v2, v3
	global_store_dwordx2 v[68:69], v[48:49], off
	v_pk_mul_f32 v[48:49], v[52:53], v[66:67] op_sel_hi:[1,0]
	v_pk_mul_f32 v[50:51], v[54:55], v[66:67] op_sel_hi:[1,0]
	global_store_dwordx2 v[68:69], v[32:33], off offset:64
	v_pk_mul_f32 v[32:33], v[36:37], v[66:67] op_sel_hi:[1,0]
	v_pk_mul_f32 v[34:35], v[38:39], v[66:67] op_sel_hi:[1,0]
	global_store_dwordx2 v[68:69], v[16:17], off offset:128
	v_pk_mul_f32 v[16:17], v[66:67], v[20:21] op_sel_hi:[0,1]
	v_pk_mul_f32 v[18:19], v[66:67], v[22:23] op_sel_hi:[0,1]
	global_store_dwordx2 v[68:69], v[0:1], off offset:192
	v_pk_mul_f32 v[0:1], v[66:67], v[4:5] op_sel_hi:[0,1]
	v_pk_mul_f32 v[2:3], v[66:67], v[6:7] op_sel_hi:[0,1]
	v_cvt_pk_bf16_f32 v48, v48, v49
	v_cvt_pk_bf16_f32 v49, v50, v51
	v_cvt_pk_bf16_f32 v32, v32, v33
	v_cvt_pk_bf16_f32 v33, v34, v35
	v_cvt_pk_bf16_f32 v16, v16, v17
	v_cvt_pk_bf16_f32 v17, v18, v19
	v_cvt_pk_bf16_f32 v0, v0, v1
	v_cvt_pk_bf16_f32 v1, v2, v3
	global_store_dwordx2 v[68:69], v[48:49], off offset:16
	v_pk_mul_f32 v[48:49], v[56:57], v[66:67] op_sel_hi:[1,0]
	v_pk_mul_f32 v[50:51], v[58:59], v[66:67] op_sel_hi:[1,0]
	global_store_dwordx2 v[68:69], v[32:33], off offset:80
	v_pk_mul_f32 v[32:33], v[40:41], v[66:67] op_sel_hi:[1,0]
	v_pk_mul_f32 v[34:35], v[42:43], v[66:67] op_sel_hi:[1,0]
	global_store_dwordx2 v[68:69], v[16:17], off offset:144
	v_pk_mul_f32 v[16:17], v[66:67], v[24:25] op_sel_hi:[0,1]
	v_pk_mul_f32 v[18:19], v[66:67], v[26:27] op_sel_hi:[0,1]
	global_store_dwordx2 v[68:69], v[0:1], off offset:208
	v_pk_mul_f32 v[0:1], v[66:67], v[8:9] op_sel_hi:[0,1]
	v_pk_mul_f32 v[2:3], v[66:67], v[10:11] op_sel_hi:[0,1]
	v_cvt_pk_bf16_f32 v48, v48, v49
	v_cvt_pk_bf16_f32 v49, v50, v51
	v_cvt_pk_bf16_f32 v32, v32, v33
	v_cvt_pk_bf16_f32 v33, v34, v35
	v_cvt_pk_bf16_f32 v16, v16, v17
	v_cvt_pk_bf16_f32 v17, v18, v19
	v_cvt_pk_bf16_f32 v0, v0, v1
	v_cvt_pk_bf16_f32 v1, v2, v3
	global_store_dwordx2 v[68:69], v[48:49], off offset:32
	v_pk_mul_f32 v[48:49], v[60:61], v[66:67] op_sel_hi:[1,0]
	v_pk_mul_f32 v[50:51], v[62:63], v[66:67] op_sel_hi:[1,0]
	global_store_dwordx2 v[68:69], v[32:33], off offset:96
	v_pk_mul_f32 v[32:33], v[44:45], v[66:67] op_sel_hi:[1,0]
	v_pk_mul_f32 v[34:35], v[46:47], v[66:67] op_sel_hi:[1,0]
	global_store_dwordx2 v[68:69], v[16:17], off offset:160
	v_pk_mul_f32 v[16:17], v[66:67], v[28:29] op_sel_hi:[0,1]
	v_pk_mul_f32 v[18:19], v[66:67], v[30:31] op_sel_hi:[0,1]
	global_store_dwordx2 v[68:69], v[0:1], off offset:224
	v_pk_mul_f32 v[0:1], v[66:67], v[12:13] op_sel_hi:[0,1]
	v_pk_mul_f32 v[2:3], v[66:67], v[14:15] op_sel_hi:[0,1]
	v_cvt_pk_bf16_f32 v48, v48, v49
	v_cvt_pk_bf16_f32 v49, v50, v51
	v_cvt_pk_bf16_f32 v32, v32, v33
	v_cvt_pk_bf16_f32 v33, v34, v35
	v_cvt_pk_bf16_f32 v16, v16, v17
	v_cvt_pk_bf16_f32 v17, v18, v19
	v_cvt_pk_bf16_f32 v0, v0, v1
	v_cvt_pk_bf16_f32 v1, v2, v3
	v_cmp_eq_u32_e32 vcc, 0, v114
	global_store_dwordx2 v[68:69], v[48:49], off offset:48
	global_store_dwordx2 v[68:69], v[32:33], off offset:112
	global_store_dwordx2 v[68:69], v[16:17], off offset:176
	global_store_dwordx2 v[68:69], v[0:1], off offset:240
	s_and_saveexec_b64 s[4:5], vcc
	s_cbranch_execz .LBB0_578
	v_log_f32_e32 v2, v64
	v_readlane_b32 s6, v240, 45
	v_lshlrev_b64 v[0:1], 5, v[108:109]
	v_readlane_b32 s7, v240, 46
	s_lshl_b32 s22, s1, 2
	v_add_f32_e32 v2, v100, v2
	v_lshl_add_u64 v[0:1], s[6:7], 0, v[0:1]
	v_lshl_add_u64 v[0:1], v[0:1], 0, s[22:23]
	global_store_dword v[0:1], v2, off
	s_branch .LBB0_578

.LBB0_1291:
	s_ashr_i32 s5, s4, 31
	s_and_b32 s6, s8, 0x700
	v_readlane_b32 s7, v240, 43
	s_lshl_b64 s[4:5], s[4:5], 11
	s_add_i32 s6, s6, s7
	s_add_u32 s4, s4, s6
	s_addc_u32 s5, s5, 0
	v_and_or_b32 v8, v15, 31, s4
	v_mov_b32_e32 v9, s5
	v_readlane_b32 s4, v240, 62
	v_lshlrev_b64 v[8:9], 10, v[8:9]
	v_readlane_b32 s5, v240, 63
	v_bfe_u32 v173, v172, 5, 1
	s_add_i32 s10, s10, s82
	v_lshl_add_u64 v[10:11], s[4:5], 0, v[8:9]
	v_readlane_b32 s4, v238, 54
	v_readlane_b32 s5, v238, 55
	v_lshl_add_u64 v[10:11], v[10:11], 0, s[22:23]
	s_nop 0
	v_lshl_add_u64 v[8:9], s[4:5], 0, v[8:9]
	v_lshl_add_u64 v[170:171], v[8:9], 0, s[22:23]
	v_lshlrev_b32_e32 v9, 8, v128
	v_add_u32_e32 v12, v13, v9
	s_waitcnt vmcnt(1)
	ds_write_b128 v12, v[74:77]
	v_add_u32_e32 v4, v16, v9
	s_waitcnt vmcnt(0)
	ds_write_b128 v4, v[78:81]
	v_lshlrev_b32_e32 v0, 4, v173
	v_mov_b32_e32 v1, v129
	v_lshl_add_u64 v[0:1], v[10:11], 0, v[0:1]
	global_load_dwordx4 v[112:115], v[0:1], off
	global_load_dwordx4 v[154:157], v[0:1], off offset:32
	global_load_dwordx4 v[150:153], v[0:1], off offset:64
	global_load_dwordx4 v[146:149], v[0:1], off offset:96
	global_load_dwordx4 v[142:145], v[0:1], off offset:128
	global_load_dwordx4 v[138:141], v[0:1], off offset:160
	global_load_dwordx4 v[134:137], v[0:1], off offset:192
	global_load_dwordx4 v[130:133], v[0:1], off offset:224
	v_lshlrev_b32_e32 v0, 8, v172
	v_lshrrev_b32_e32 v8, 5, v172
	v_and_b32_e32 v0, 0x1f00, v0
	v_add_u32_e32 v4, 0, v0
	v_bitop3_b32 v0, v8, v14, 1 bitop3:0x6c
	v_lshl_add_u32 v116, v0, 4, v4
	s_waitcnt lgkmcnt(0)
	s_barrier
	ds_read_b128 v[0:3], v116
	s_mov_b32 s4, 0xff800000
	v_lshlrev_b32_e32 v128, 3, v173
	s_waitcnt vmcnt(7) lgkmcnt(0)
	v_mfma_f32_32x32x16_bf16 v[48:63], v[0:3], v[112:115], 0
	v_bitop3_b32 v0, v173, v14, 2 bitop3:0x36
	v_lshl_add_u32 v164, v0, 4, v4
	ds_read_b128 v[0:3], v164
	ds_read_b128 v[64:67], v164 offset:24576
	ds_read_b128 v[80:83], v164 offset:32768
	ds_read_b128 v[96:99], v164 offset:40960
	ds_read_b128 v[118:121], v164 offset:49152
	s_waitcnt vmcnt(6) lgkmcnt(4)
	v_mfma_f32_32x32x16_bf16 v[48:63], v[0:3], v[154:157], v[48:63]
	v_bitop3_b32 v0, v173, v14, 4 bitop3:0x36
	v_lshl_add_u32 v163, v0, 4, v4
	ds_read_b128 v[0:3], v163
	s_waitcnt vmcnt(5) lgkmcnt(0)
	v_mfma_f32_32x32x16_bf16 v[48:63], v[0:3], v[150:153], v[48:63]
	v_bitop3_b32 v0, v173, v14, 6 bitop3:0x36
	v_lshl_add_u32 v162, v0, 4, v4
	ds_read_b128 v[0:3], v162
	s_waitcnt vmcnt(4) lgkmcnt(0)
	v_mfma_f32_32x32x16_bf16 v[48:63], v[0:3], v[146:149], v[48:63]
	v_bitop3_b32 v0, v173, v14, 8 bitop3:0x36
	v_lshl_add_u32 v161, v0, 4, v4
	ds_read_b128 v[0:3], v161
	s_waitcnt vmcnt(3) lgkmcnt(0)
	v_mfma_f32_32x32x16_bf16 v[48:63], v[0:3], v[142:145], v[48:63]
	v_bitop3_b32 v0, v173, v14, 10 bitop3:0x36
	v_lshl_add_u32 v160, v0, 4, v4
	ds_read_b128 v[0:3], v160
	s_waitcnt vmcnt(2) lgkmcnt(0)
	v_mfma_f32_32x32x16_bf16 v[48:63], v[0:3], v[138:141], v[48:63]
	v_bitop3_b32 v0, v173, v14, 12 bitop3:0x36
	v_lshl_add_u32 v159, v0, 4, v4
	ds_read_b128 v[0:3], v159
	s_waitcnt vmcnt(1) lgkmcnt(0)
	v_mfma_f32_32x32x16_bf16 v[48:63], v[0:3], v[134:137], v[48:63]
	v_bitop3_b32 v0, v173, v14, 14 bitop3:0x36
	v_lshl_add_u32 v158, v0, 4, v4
	ds_read_b128 v[0:3], v158
	s_waitcnt vmcnt(0) lgkmcnt(0)
	v_mfma_f32_32x32x16_bf16 v[48:63], v[0:3], v[130:133], v[48:63]
	ds_read_b128 v[242:245], v116 offset:8192
	ds_read_b128 v[246:249], v164 offset:8192
	ds_read_b128 v[250:253], v163 offset:8192
	s_waitcnt lgkmcnt(2)
	v_mfma_f32_32x32x16_bf16 v[32:47], v[242:245], v[112:115], 0
	ds_read_b128 v[242:245], v162 offset:8192
	s_waitcnt lgkmcnt(2)
	v_mfma_f32_32x32x16_bf16 v[32:47], v[246:249], v[154:157], v[32:47]
	ds_read_b128 v[246:249], v161 offset:8192
	s_waitcnt lgkmcnt(2)
	v_mfma_f32_32x32x16_bf16 v[32:47], v[250:253], v[150:153], v[32:47]
	ds_read_b128 v[250:253], v160 offset:8192
	s_waitcnt lgkmcnt(2)
	v_mfma_f32_32x32x16_bf16 v[32:47], v[242:245], v[146:149], v[32:47]
	ds_read_b128 v[242:245], v159 offset:8192
	s_waitcnt lgkmcnt(2)
	v_mfma_f32_32x32x16_bf16 v[32:47], v[246:249], v[142:145], v[32:47]
	ds_read_b128 v[246:249], v158 offset:8192
	s_waitcnt lgkmcnt(2)
	v_mfma_f32_32x32x16_bf16 v[32:47], v[250:253], v[138:141], v[32:47]
	ds_read_b128 v[250:253], v116 offset:16384
	s_waitcnt lgkmcnt(2)
	v_mfma_f32_32x32x16_bf16 v[32:47], v[242:245], v[134:137], v[32:47]
	s_waitcnt lgkmcnt(1)
	v_mfma_f32_32x32x16_bf16 v[32:47], v[246:249], v[130:133], v[32:47]
	s_waitcnt lgkmcnt(0)
	v_mfma_f32_32x32x16_bf16 v[16:31], v[250:253], v[112:115], 0
	ds_read_b128 v[0:3], v164 offset:16384
	ds_read_b128 v[164:167], v164 offset:57344
	s_waitcnt lgkmcnt(1)
	v_mfma_f32_32x32x16_bf16 v[16:31], v[0:3], v[154:157], v[16:31]
	ds_read_b128 v[242:245], v163 offset:16384
	ds_read_b128 v[246:249], v162 offset:16384
	ds_read_b128 v[250:253], v161 offset:16384
	s_waitcnt lgkmcnt(2)
	v_mfma_f32_32x32x16_bf16 v[16:31], v[242:245], v[150:153], v[16:31]
	ds_read_b128 v[242:245], v160 offset:16384
	s_waitcnt lgkmcnt(2)
	v_mfma_f32_32x32x16_bf16 v[16:31], v[246:249], v[146:149], v[16:31]
	ds_read_b128 v[246:249], v159 offset:16384
	s_waitcnt lgkmcnt(2)
	v_mfma_f32_32x32x16_bf16 v[16:31], v[250:253], v[142:145], v[16:31]
	ds_read_b128 v[250:253], v158 offset:16384
	s_waitcnt lgkmcnt(2)
	v_mfma_f32_32x32x16_bf16 v[16:31], v[242:245], v[138:141], v[16:31]
	ds_read_b128 v[242:245], v116 offset:24576
	s_waitcnt lgkmcnt(2)
	v_mfma_f32_32x32x16_bf16 v[16:31], v[246:249], v[134:137], v[16:31]
	ds_read_b128 v[246:249], v163 offset:24576
	s_waitcnt lgkmcnt(2)
	v_mfma_f32_32x32x16_bf16 v[16:31], v[250:253], v[130:133], v[16:31]
	ds_read_b128 v[250:253], v162 offset:24576
	s_waitcnt lgkmcnt(2)
	v_mfma_f32_32x32x16_bf16 v[0:15], v[242:245], v[112:115], 0
	v_mfma_f32_32x32x16_bf16 v[0:15], v[64:67], v[154:157], v[0:15]
	ds_read_b128 v[242:245], v161 offset:24576
	s_waitcnt lgkmcnt(2)
	v_mfma_f32_32x32x16_bf16 v[0:15], v[246:249], v[150:153], v[0:15]
	ds_read_b128 v[246:249], v160 offset:24576
	s_waitcnt lgkmcnt(2)
	v_mfma_f32_32x32x16_bf16 v[0:15], v[250:253], v[146:149], v[0:15]
	ds_read_b128 v[250:253], v159 offset:24576
	s_waitcnt lgkmcnt(2)
	v_mfma_f32_32x32x16_bf16 v[0:15], v[242:245], v[142:145], v[0:15]
	ds_read_b128 v[242:245], v158 offset:24576
	s_waitcnt lgkmcnt(2)
	v_mfma_f32_32x32x16_bf16 v[0:15], v[246:249], v[138:141], v[0:15]
	ds_read_b128 v[246:249], v116 offset:32768
	s_waitcnt lgkmcnt(2)
	v_mfma_f32_32x32x16_bf16 v[0:15], v[250:253], v[134:137], v[0:15]
	ds_read_b128 v[250:253], v163 offset:32768
	s_waitcnt lgkmcnt(2)
	v_mfma_f32_32x32x16_bf16 v[0:15], v[242:245], v[130:133], v[0:15]
	ds_read_b128 v[242:245], v162 offset:32768
	s_waitcnt lgkmcnt(2)
	v_mfma_f32_32x32x16_bf16 v[64:79], v[246:249], v[112:115], 0
	v_mfma_f32_32x32x16_bf16 v[64:79], v[80:83], v[154:157], v[64:79]
	ds_read_b128 v[246:249], v161 offset:32768
	s_waitcnt lgkmcnt(2)
	v_mfma_f32_32x32x16_bf16 v[64:79], v[250:253], v[150:153], v[64:79]
	ds_read_b128 v[250:253], v160 offset:32768
	s_waitcnt lgkmcnt(2)
	v_mfma_f32_32x32x16_bf16 v[64:79], v[242:245], v[146:149], v[64:79]
	ds_read_b128 v[242:245], v159 offset:32768
	s_waitcnt lgkmcnt(2)
	v_mfma_f32_32x32x16_bf16 v[64:79], v[246:249], v[142:145], v[64:79]
	ds_read_b128 v[246:249], v158 offset:32768
	s_waitcnt lgkmcnt(2)
	v_mfma_f32_32x32x16_bf16 v[64:79], v[250:253], v[138:141], v[64:79]
	ds_read_b128 v[250:253], v116 offset:40960
	s_waitcnt lgkmcnt(2)
	v_mfma_f32_32x32x16_bf16 v[64:79], v[242:245], v[134:137], v[64:79]
	ds_read_b128 v[242:245], v163 offset:40960
	s_waitcnt lgkmcnt(2)
	v_mfma_f32_32x32x16_bf16 v[64:79], v[246:249], v[130:133], v[64:79]
	ds_read_b128 v[246:249], v162 offset:40960
	s_waitcnt lgkmcnt(2)
	v_mfma_f32_32x32x16_bf16 v[80:95], v[250:253], v[112:115], 0
	v_mfma_f32_32x32x16_bf16 v[80:95], v[96:99], v[154:157], v[80:95]
	ds_read_b128 v[250:253], v161 offset:40960
	s_waitcnt lgkmcnt(2)
	v_mfma_f32_32x32x16_bf16 v[80:95], v[242:245], v[150:153], v[80:95]
	ds_read_b128 v[242:245], v160 offset:40960
	s_waitcnt lgkmcnt(2)
	v_mfma_f32_32x32x16_bf16 v[80:95], v[246:249], v[146:149], v[80:95]
	ds_read_b128 v[246:249], v159 offset:40960
	s_waitcnt lgkmcnt(2)
	v_mfma_f32_32x32x16_bf16 v[80:95], v[250:253], v[142:145], v[80:95]
	ds_read_b128 v[250:253], v158 offset:40960
	s_waitcnt lgkmcnt(2)
	v_mfma_f32_32x32x16_bf16 v[80:95], v[242:245], v[138:141], v[80:95]
	ds_read_b128 v[242:245], v116 offset:49152
	s_waitcnt lgkmcnt(2)
	v_mfma_f32_32x32x16_bf16 v[80:95], v[246:249], v[134:137], v[80:95]
	ds_read_b128 v[246:249], v163 offset:49152
	s_waitcnt lgkmcnt(2)
	v_mfma_f32_32x32x16_bf16 v[80:95], v[250:253], v[130:133], v[80:95]
	ds_read_b128 v[250:253], v162 offset:49152
	s_waitcnt lgkmcnt(2)
	v_mfma_f32_32x32x16_bf16 v[96:111], v[242:245], v[112:115], 0
	v_mfma_f32_32x32x16_bf16 v[96:111], v[118:121], v[154:157], v[96:111]
	ds_read_b128 v[242:245], v161 offset:49152
	s_waitcnt lgkmcnt(2)
	v_mfma_f32_32x32x16_bf16 v[96:111], v[246:249], v[150:153], v[96:111]
	ds_read_b128 v[246:249], v160 offset:49152
	s_waitcnt lgkmcnt(2)
	v_mfma_f32_32x32x16_bf16 v[96:111], v[250:253], v[146:149], v[96:111]
	ds_read_b128 v[250:253], v159 offset:49152
	s_waitcnt lgkmcnt(2)
	v_mfma_f32_32x32x16_bf16 v[96:111], v[242:245], v[142:145], v[96:111]
	ds_read_b128 v[242:245], v158 offset:49152
	s_waitcnt lgkmcnt(2)
	v_mfma_f32_32x32x16_bf16 v[96:111], v[246:249], v[138:141], v[96:111]
	ds_read_b128 v[246:249], v116 offset:57344
	s_waitcnt lgkmcnt(2)
	v_mfma_f32_32x32x16_bf16 v[96:111], v[250:253], v[134:137], v[96:111]
	ds_read_b128 v[250:253], v163 offset:57344
	s_waitcnt lgkmcnt(2)
	v_mfma_f32_32x32x16_bf16 v[96:111], v[242:245], v[130:133], v[96:111]
	ds_read_b128 v[242:245], v162 offset:57344
	s_waitcnt lgkmcnt(2)
	v_mfma_f32_32x32x16_bf16 v[112:127], v[246:249], v[112:115], 0
	v_mfma_f32_32x32x16_bf16 v[112:127], v[164:167], v[154:157], v[112:127]
	ds_read_b128 v[246:249], v161 offset:57344
	s_waitcnt lgkmcnt(2)
	v_mfma_f32_32x32x16_bf16 v[112:127], v[250:253], v[150:153], v[112:127]
	ds_read_b128 v[250:253], v160 offset:57344
	s_waitcnt lgkmcnt(2)
	v_mfma_f32_32x32x16_bf16 v[112:127], v[242:245], v[146:149], v[112:127]
	ds_read_b128 v[242:245], v159 offset:57344
	s_waitcnt lgkmcnt(2)
	v_mfma_f32_32x32x16_bf16 v[112:127], v[246:249], v[142:145], v[112:127]
	ds_read_b128 v[246:249], v158 offset:57344
	s_waitcnt lgkmcnt(2)
	v_mfma_f32_32x32x16_bf16 v[112:127], v[250:253], v[138:141], v[112:127]
	s_waitcnt lgkmcnt(1)
	v_mfma_f32_32x32x16_bf16 v[112:127], v[242:245], v[134:137], v[112:127]
	s_waitcnt lgkmcnt(0)
	v_mfma_f32_32x32x16_bf16 v[112:127], v[246:249], v[130:133], v[112:127]
	v_max3_f32 v130, v48, s4, v49
	v_max3_f32 v130, v130, v50, v51
	v_max3_f32 v130, v130, v52, v53
	v_max3_f32 v130, v130, v54, v55
	v_max3_f32 v130, v130, v56, v57
	v_max3_f32 v130, v130, v58, v59
	v_max3_f32 v130, v130, v60, v61
	v_max3_f32 v130, v130, v62, v63
	v_max3_f32 v130, v130, v32, v33
	v_max3_f32 v130, v130, v34, v35
	v_max3_f32 v130, v130, v36, v37
	v_max3_f32 v130, v130, v38, v39
	v_max3_f32 v130, v130, v40, v41
	v_max3_f32 v130, v130, v42, v43
	v_max3_f32 v130, v130, v44, v45
	v_max3_f32 v130, v130, v46, v47
	v_max3_f32 v130, v130, v16, v17
	v_max3_f32 v130, v130, v18, v19
	v_max3_f32 v130, v130, v20, v21
	v_max3_f32 v130, v130, v22, v23
	v_max3_f32 v130, v130, v24, v25
	v_max3_f32 v130, v130, v26, v27
	v_max3_f32 v130, v130, v28, v29
	v_max3_f32 v130, v130, v30, v31
	v_max3_f32 v130, v130, v0, v1
	v_max3_f32 v130, v130, v2, v3
	v_max3_f32 v130, v130, v4, v5
	v_max3_f32 v130, v130, v6, v7
	v_max3_f32 v130, v130, v8, v9
	v_max3_f32 v130, v130, v10, v11
	v_max3_f32 v130, v130, v12, v13
	v_max3_f32 v130, v130, v14, v15
	v_max3_f32 v130, v130, v64, v65
	v_max3_f32 v130, v130, v66, v67
	v_max3_f32 v130, v130, v68, v69
	v_max3_f32 v130, v130, v70, v71
	v_max3_f32 v130, v130, v72, v73
	v_max3_f32 v130, v130, v74, v75
	v_max3_f32 v130, v130, v76, v77
	v_max3_f32 v130, v130, v78, v79
	v_max3_f32 v130, v130, v80, v81
	v_max3_f32 v130, v130, v82, v83
	v_max3_f32 v130, v130, v84, v85
	v_max3_f32 v130, v130, v86, v87
	v_max3_f32 v130, v130, v88, v89
	v_max3_f32 v130, v130, v90, v91
	v_max3_f32 v130, v130, v92, v93
	v_max3_f32 v130, v130, v94, v95
	v_max3_f32 v130, v130, v96, v97
	v_max3_f32 v130, v130, v98, v99
	v_max3_f32 v130, v130, v100, v101
	v_max3_f32 v130, v130, v102, v103
	v_max3_f32 v130, v130, v104, v105
	v_max3_f32 v130, v130, v106, v107
	v_max3_f32 v130, v130, v108, v109
	v_max3_f32 v130, v130, v110, v111
	v_max3_f32 v130, v130, v112, v113
	v_max3_f32 v130, v130, v114, v115
	v_max3_f32 v130, v130, v116, v117
	v_max3_f32 v130, v130, v118, v119
	v_and_b32_e32 v132, 64, v214
	v_max3_f32 v130, v130, v120, v121
	v_xor_b32_e32 v131, 32, v214
	v_add_u32_e32 v132, 64, v132
	v_max3_f32 v130, v130, v122, v123
	v_cmp_lt_i32_e32 vcc, v131, v132
	v_max3_f32 v130, v130, v124, v125
	v_max3_f32 v130, v130, v126, v127
	v_cndmask_b32_e32 v131, v214, v131, vcc
	v_lshlrev_b32_e32 v174, 2, v131
	ds_bpermute_b32 v131, v174, v130
	s_waitcnt lgkmcnt(0)
	v_max_f32_e32 v131, v131, v131
	v_max_f32_e32 v175, v130, v131
	v_sub_f32_e32 v48, v48, v175
	v_exp_f32_e32 v48, v48
	v_sub_f32_e32 v49, v49, v175
	v_exp_f32_e32 v49, v49
	v_sub_f32_e32 v50, v50, v175
	v_exp_f32_e32 v50, v50
	v_sub_f32_e32 v51, v51, v175
	v_exp_f32_e32 v51, v51
	v_sub_f32_e32 v52, v52, v175
	v_add_f32_e32 v130, 0, v48
	v_exp_f32_e32 v52, v52
	v_sub_f32_e32 v53, v53, v175
	v_add_f32_e32 v130, v49, v130
	v_exp_f32_e32 v53, v53
	v_sub_f32_e32 v54, v54, v175
	v_add_f32_e32 v130, v50, v130
	v_exp_f32_e32 v54, v54
	v_sub_f32_e32 v55, v55, v175
	v_add_f32_e32 v130, v51, v130
	v_exp_f32_e32 v55, v55
	v_cvt_pk_bf16_f32 v166, v48, v49
	v_sub_f32_e32 v48, v56, v175
	v_add_f32_e32 v130, v52, v130
	v_cvt_pk_bf16_f32 v167, v50, v51
	v_exp_f32_e32 v48, v48
	v_sub_f32_e32 v50, v57, v175
	v_add_f32_e32 v130, v53, v130
	v_exp_f32_e32 v50, v50
	v_sub_f32_e32 v51, v58, v175
	v_add_f32_e32 v130, v54, v130
	v_cvt_pk_bf16_f32 v168, v52, v53
	v_exp_f32_e32 v51, v51
	v_sub_f32_e32 v52, v59, v175
	v_add_f32_e32 v130, v55, v130
	v_exp_f32_e32 v52, v52
	v_sub_f32_e32 v53, v60, v175
	v_cvt_pk_bf16_f32 v169, v54, v55
	v_add_f32_e32 v49, v48, v130
	v_exp_f32_e32 v53, v53
	v_sub_f32_e32 v54, v61, v175
	v_add_f32_e32 v49, v50, v49
	v_exp_f32_e32 v54, v54
	v_sub_f32_e32 v55, v62, v175
	v_add_f32_e32 v49, v51, v49
	v_exp_f32_e32 v55, v55
	v_sub_f32_e32 v56, v63, v175
	v_add_f32_e32 v49, v52, v49
	v_exp_f32_e32 v56, v56
	v_sub_f32_e32 v32, v32, v175
	v_add_f32_e32 v49, v53, v49
	v_exp_f32_e32 v32, v32
	v_sub_f32_e32 v33, v33, v175
	v_add_f32_e32 v49, v54, v49
	v_exp_f32_e32 v33, v33
	v_sub_f32_e32 v34, v34, v175
	v_add_f32_e32 v49, v55, v49
	v_exp_f32_e32 v34, v34
	v_sub_f32_e32 v35, v35, v175
	v_add_f32_e32 v49, v56, v49
	v_exp_f32_e32 v35, v35
	v_sub_f32_e32 v36, v36, v175
	v_cvt_pk_bf16_f32 v162, v48, v50
	v_add_f32_e32 v48, v32, v49
	v_exp_f32_e32 v36, v36
	v_sub_f32_e32 v37, v37, v175
	v_add_f32_e32 v48, v33, v48
	v_exp_f32_e32 v37, v37
	v_sub_f32_e32 v38, v38, v175
	v_add_f32_e32 v48, v34, v48
	v_exp_f32_e32 v38, v38
	v_sub_f32_e32 v39, v39, v175
	v_add_f32_e32 v48, v35, v48
	v_exp_f32_e32 v39, v39
	v_cvt_pk_bf16_f32 v158, v32, v33
	v_sub_f32_e32 v32, v40, v175
	v_add_f32_e32 v48, v36, v48
	v_cvt_pk_bf16_f32 v159, v34, v35
	v_exp_f32_e32 v32, v32
	v_sub_f32_e32 v34, v41, v175
	v_add_f32_e32 v48, v37, v48
	v_exp_f32_e32 v34, v34
	v_sub_f32_e32 v35, v42, v175
	v_add_f32_e32 v48, v38, v48
	v_cvt_pk_bf16_f32 v160, v36, v37
	v_exp_f32_e32 v35, v35
	v_sub_f32_e32 v36, v43, v175
	v_add_f32_e32 v48, v39, v48
	v_exp_f32_e32 v36, v36
	v_sub_f32_e32 v37, v44, v175
	v_cvt_pk_bf16_f32 v161, v38, v39
	v_add_f32_e32 v33, v32, v48
	v_exp_f32_e32 v37, v37
	v_sub_f32_e32 v38, v45, v175
	v_add_f32_e32 v33, v34, v33
	v_exp_f32_e32 v38, v38
	v_sub_f32_e32 v39, v46, v175
	v_add_f32_e32 v33, v35, v33
	v_exp_f32_e32 v39, v39
	v_sub_f32_e32 v40, v47, v175
	v_add_f32_e32 v33, v36, v33
	v_exp_f32_e32 v40, v40
	v_sub_f32_e32 v16, v16, v175
	v_add_f32_e32 v33, v37, v33
	v_exp_f32_e32 v16, v16
	v_sub_f32_e32 v17, v17, v175
	v_add_f32_e32 v33, v38, v33
	v_exp_f32_e32 v17, v17
	v_sub_f32_e32 v18, v18, v175
	v_add_f32_e32 v33, v39, v33
	v_exp_f32_e32 v18, v18
	v_sub_f32_e32 v19, v19, v175
	v_add_f32_e32 v33, v40, v33
	v_exp_f32_e32 v19, v19
	v_sub_f32_e32 v20, v20, v175
	v_cvt_pk_bf16_f32 v154, v32, v34
	v_add_f32_e32 v32, v16, v33
	v_exp_f32_e32 v20, v20
	v_sub_f32_e32 v21, v21, v175
	v_add_f32_e32 v32, v17, v32
	v_exp_f32_e32 v21, v21
	v_sub_f32_e32 v22, v22, v175
	v_add_f32_e32 v32, v18, v32
	v_exp_f32_e32 v22, v22
	v_sub_f32_e32 v23, v23, v175
	v_add_f32_e32 v32, v19, v32
	v_exp_f32_e32 v23, v23
	v_cvt_pk_bf16_f32 v150, v16, v17
	v_sub_f32_e32 v16, v24, v175
	v_add_f32_e32 v32, v20, v32
	v_cvt_pk_bf16_f32 v151, v18, v19
	v_exp_f32_e32 v16, v16
	v_sub_f32_e32 v18, v25, v175
	v_add_f32_e32 v32, v21, v32
	v_exp_f32_e32 v18, v18
	v_sub_f32_e32 v19, v26, v175
	v_add_f32_e32 v32, v22, v32
	v_cvt_pk_bf16_f32 v152, v20, v21
	v_exp_f32_e32 v19, v19
	v_sub_f32_e32 v20, v27, v175
	v_add_f32_e32 v32, v23, v32
	v_exp_f32_e32 v20, v20
	v_sub_f32_e32 v21, v28, v175
	v_cvt_pk_bf16_f32 v153, v22, v23
	v_add_f32_e32 v17, v16, v32
	v_exp_f32_e32 v21, v21
	v_sub_f32_e32 v22, v29, v175
	v_add_f32_e32 v17, v18, v17
	v_exp_f32_e32 v22, v22
	v_sub_f32_e32 v23, v30, v175
	v_add_f32_e32 v17, v19, v17
	v_exp_f32_e32 v23, v23
	v_sub_f32_e32 v24, v31, v175
	v_add_f32_e32 v17, v20, v17
	v_exp_f32_e32 v24, v24
	v_sub_f32_e32 v0, v0, v175
	v_add_f32_e32 v17, v21, v17
	v_exp_f32_e32 v0, v0
	v_sub_f32_e32 v1, v1, v175
	v_add_f32_e32 v17, v22, v17
	v_exp_f32_e32 v1, v1
	v_sub_f32_e32 v2, v2, v175
	v_add_f32_e32 v17, v23, v17
	v_exp_f32_e32 v2, v2
	v_sub_f32_e32 v3, v3, v175
	v_add_f32_e32 v17, v24, v17
	v_exp_f32_e32 v3, v3
	v_sub_f32_e32 v4, v4, v175
	v_cvt_pk_bf16_f32 v146, v16, v18
	v_add_f32_e32 v16, v0, v17
	v_exp_f32_e32 v4, v4
	v_sub_f32_e32 v5, v5, v175
	v_add_f32_e32 v16, v1, v16
	v_exp_f32_e32 v5, v5
	v_sub_f32_e32 v6, v6, v175
	v_add_f32_e32 v16, v2, v16
	v_exp_f32_e32 v6, v6
	v_sub_f32_e32 v7, v7, v175
	v_add_f32_e32 v16, v3, v16
	v_exp_f32_e32 v7, v7
	v_cvt_pk_bf16_f32 v142, v0, v1
	v_sub_f32_e32 v0, v8, v175
	v_add_f32_e32 v16, v4, v16
	v_cvt_pk_bf16_f32 v143, v2, v3
	v_exp_f32_e32 v0, v0
	v_sub_f32_e32 v2, v9, v175
	v_add_f32_e32 v16, v5, v16
	v_exp_f32_e32 v2, v2
	v_sub_f32_e32 v3, v10, v175
	v_add_f32_e32 v16, v6, v16
	v_cvt_pk_bf16_f32 v144, v4, v5
	v_exp_f32_e32 v3, v3
	v_sub_f32_e32 v4, v11, v175
	v_add_f32_e32 v16, v7, v16
	v_exp_f32_e32 v4, v4
	v_sub_f32_e32 v5, v12, v175
	v_cvt_pk_bf16_f32 v145, v6, v7
	v_add_f32_e32 v1, v0, v16
	v_exp_f32_e32 v5, v5
	v_sub_f32_e32 v6, v13, v175
	v_add_f32_e32 v1, v2, v1
	v_exp_f32_e32 v6, v6
	v_sub_f32_e32 v7, v14, v175
	v_add_f32_e32 v1, v3, v1
	v_exp_f32_e32 v7, v7
	v_sub_f32_e32 v8, v15, v175
	v_add_f32_e32 v1, v4, v1
	v_exp_f32_e32 v8, v8
	v_cvt_pk_bf16_f32 v138, v0, v2
	v_sub_f32_e32 v0, v64, v175
	v_add_f32_e32 v1, v5, v1
	v_exp_f32_e32 v0, v0
	v_sub_f32_e32 v2, v65, v175
	v_add_f32_e32 v1, v6, v1
	v_cvt_pk_bf16_f32 v139, v3, v4
	v_exp_f32_e32 v2, v2
	v_sub_f32_e32 v3, v66, v175
	v_add_f32_e32 v1, v7, v1
	v_exp_f32_e32 v3, v3
	v_sub_f32_e32 v4, v67, v175
	v_add_f32_e32 v1, v8, v1
	v_cvt_pk_bf16_f32 v140, v5, v6
	v_exp_f32_e32 v4, v4
	v_sub_f32_e32 v5, v68, v175
	v_add_f32_e32 v1, v0, v1
	v_exp_f32_e32 v5, v5
	v_sub_f32_e32 v6, v69, v175
	v_cvt_pk_bf16_f32 v141, v7, v8
	v_add_f32_e32 v1, v2, v1
	v_exp_f32_e32 v6, v6
	v_sub_f32_e32 v7, v70, v175
	v_add_f32_e32 v1, v3, v1
	v_exp_f32_e32 v7, v7
	v_sub_f32_e32 v8, v71, v175
	v_add_f32_e32 v1, v4, v1
	v_exp_f32_e32 v8, v8
	v_cvt_pk_bf16_f32 v134, v0, v2
	v_sub_f32_e32 v0, v72, v175
	v_add_f32_e32 v1, v5, v1
	v_exp_f32_e32 v0, v0
	v_sub_f32_e32 v2, v73, v175
	v_add_f32_e32 v1, v6, v1
	v_cvt_pk_bf16_f32 v135, v3, v4
	v_exp_f32_e32 v2, v2
	v_sub_f32_e32 v3, v74, v175
	v_add_f32_e32 v1, v7, v1
	v_exp_f32_e32 v3, v3
	v_sub_f32_e32 v4, v75, v175
	v_add_f32_e32 v1, v8, v1
	v_cvt_pk_bf16_f32 v136, v5, v6
	v_exp_f32_e32 v4, v4
	v_sub_f32_e32 v5, v76, v175
	v_add_f32_e32 v1, v0, v1
	v_exp_f32_e32 v5, v5
	v_sub_f32_e32 v6, v77, v175
	v_cvt_pk_bf16_f32 v137, v7, v8
	v_add_f32_e32 v1, v2, v1
	v_exp_f32_e32 v6, v6
	v_sub_f32_e32 v7, v78, v175
	v_add_f32_e32 v1, v3, v1
	v_exp_f32_e32 v7, v7
	v_sub_f32_e32 v8, v79, v175
	v_add_f32_e32 v1, v4, v1
	v_exp_f32_e32 v8, v8
	v_cvt_pk_bf16_f32 v130, v0, v2
	v_sub_f32_e32 v0, v80, v175
	v_add_f32_e32 v1, v5, v1
	v_exp_f32_e32 v0, v0
	v_sub_f32_e32 v2, v81, v175
	v_add_f32_e32 v1, v6, v1
	v_cvt_pk_bf16_f32 v131, v3, v4
	v_exp_f32_e32 v2, v2
	v_sub_f32_e32 v3, v82, v175
	v_add_f32_e32 v1, v7, v1
	v_exp_f32_e32 v3, v3
	v_sub_f32_e32 v4, v83, v175
	v_add_f32_e32 v1, v8, v1
	v_cvt_pk_bf16_f32 v132, v5, v6
	v_exp_f32_e32 v4, v4
	v_sub_f32_e32 v5, v84, v175
	v_add_f32_e32 v1, v0, v1
	v_exp_f32_e32 v5, v5
	v_sub_f32_e32 v6, v85, v175
	v_cvt_pk_bf16_f32 v133, v7, v8
	v_add_f32_e32 v1, v2, v1
	v_exp_f32_e32 v6, v6
	v_sub_f32_e32 v7, v86, v175
	v_add_f32_e32 v1, v3, v1
	v_exp_f32_e32 v7, v7
	v_sub_f32_e32 v8, v87, v175
	v_add_f32_e32 v1, v4, v1
	v_exp_f32_e32 v8, v8
	v_cvt_pk_bf16_f32 v84, v0, v2
	v_sub_f32_e32 v0, v88, v175
	v_add_f32_e32 v1, v5, v1
	v_exp_f32_e32 v0, v0
	v_sub_f32_e32 v2, v89, v175
	v_add_f32_e32 v1, v6, v1
	v_cvt_pk_bf16_f32 v85, v3, v4
	v_exp_f32_e32 v2, v2
	v_sub_f32_e32 v3, v90, v175
	v_add_f32_e32 v1, v7, v1
	v_exp_f32_e32 v3, v3
	v_sub_f32_e32 v4, v91, v175
	v_add_f32_e32 v1, v8, v1
	v_cvt_pk_bf16_f32 v86, v5, v6
	v_exp_f32_e32 v4, v4
	v_sub_f32_e32 v5, v92, v175
	v_add_f32_e32 v1, v0, v1
	v_exp_f32_e32 v5, v5
	v_sub_f32_e32 v6, v93, v175
	v_cvt_pk_bf16_f32 v87, v7, v8
	v_add_f32_e32 v1, v2, v1
	v_exp_f32_e32 v6, v6
	v_sub_f32_e32 v7, v94, v175
	v_add_f32_e32 v1, v3, v1
	v_exp_f32_e32 v7, v7
	v_sub_f32_e32 v8, v95, v175
	v_add_f32_e32 v1, v4, v1
	v_exp_f32_e32 v8, v8
	v_cvt_pk_bf16_f32 v80, v0, v2
	v_sub_f32_e32 v0, v96, v175
	v_add_f32_e32 v1, v5, v1
	v_exp_f32_e32 v0, v0
	v_sub_f32_e32 v2, v97, v175
	v_add_f32_e32 v1, v6, v1
	v_cvt_pk_bf16_f32 v81, v3, v4
	v_exp_f32_e32 v2, v2
	v_sub_f32_e32 v3, v98, v175
	v_add_f32_e32 v1, v7, v1
	v_exp_f32_e32 v3, v3
	v_sub_f32_e32 v4, v99, v175
	v_add_f32_e32 v1, v8, v1
	v_cvt_pk_bf16_f32 v82, v5, v6
	v_exp_f32_e32 v4, v4
	v_sub_f32_e32 v5, v100, v175
	v_add_f32_e32 v1, v0, v1
	v_exp_f32_e32 v5, v5
	v_sub_f32_e32 v6, v101, v175
	v_cvt_pk_bf16_f32 v83, v7, v8
	v_add_f32_e32 v1, v2, v1
	v_exp_f32_e32 v6, v6
	v_sub_f32_e32 v7, v102, v175
	v_add_f32_e32 v1, v3, v1
	v_exp_f32_e32 v7, v7
	v_sub_f32_e32 v8, v103, v175
	v_add_f32_e32 v1, v4, v1
	v_exp_f32_e32 v8, v8
	v_cvt_pk_bf16_f32 v76, v0, v2
	v_sub_f32_e32 v0, v104, v175
	v_add_f32_e32 v1, v5, v1
	v_exp_f32_e32 v0, v0
	v_sub_f32_e32 v2, v105, v175
	v_add_f32_e32 v1, v6, v1
	v_cvt_pk_bf16_f32 v77, v3, v4
	v_exp_f32_e32 v2, v2
	v_sub_f32_e32 v3, v106, v175
	v_add_f32_e32 v1, v7, v1
	v_exp_f32_e32 v3, v3
	v_sub_f32_e32 v4, v107, v175
	v_add_f32_e32 v1, v8, v1
	v_cvt_pk_bf16_f32 v78, v5, v6
	v_exp_f32_e32 v4, v4
	v_sub_f32_e32 v5, v108, v175
	v_add_f32_e32 v1, v0, v1
	v_exp_f32_e32 v5, v5
	v_sub_f32_e32 v6, v109, v175
	v_cvt_pk_bf16_f32 v79, v7, v8
	v_add_f32_e32 v1, v2, v1
	v_exp_f32_e32 v6, v6
	v_sub_f32_e32 v7, v110, v175
	v_add_f32_e32 v1, v3, v1
	v_exp_f32_e32 v7, v7
	v_sub_f32_e32 v8, v111, v175
	v_add_f32_e32 v1, v4, v1
	v_exp_f32_e32 v8, v8
	v_cvt_pk_bf16_f32 v68, v0, v2
	v_sub_f32_e32 v0, v112, v175
	v_add_f32_e32 v1, v5, v1
	v_exp_f32_e32 v0, v0
	v_sub_f32_e32 v2, v113, v175
	v_add_f32_e32 v1, v6, v1
	v_cvt_pk_bf16_f32 v69, v3, v4
	v_exp_f32_e32 v2, v2
	v_sub_f32_e32 v3, v114, v175
	v_add_f32_e32 v1, v7, v1
	v_exp_f32_e32 v3, v3
	v_sub_f32_e32 v4, v115, v175
	v_add_f32_e32 v1, v8, v1
	v_cvt_pk_bf16_f32 v70, v5, v6
	v_exp_f32_e32 v4, v4
	v_sub_f32_e32 v5, v116, v175
	v_add_f32_e32 v1, v0, v1
	v_exp_f32_e32 v5, v5
	v_sub_f32_e32 v6, v117, v175
	v_cvt_pk_bf16_f32 v71, v7, v8
	v_add_f32_e32 v1, v2, v1
	v_exp_f32_e32 v6, v6
	v_sub_f32_e32 v7, v118, v175
	v_add_f32_e32 v1, v3, v1
	v_exp_f32_e32 v7, v7
	v_sub_f32_e32 v8, v119, v175
	v_add_f32_e32 v1, v4, v1
	v_exp_f32_e32 v8, v8
	v_cvt_pk_bf16_f32 v72, v0, v2
	v_sub_f32_e32 v0, v120, v175
	v_add_f32_e32 v1, v5, v1
	v_exp_f32_e32 v0, v0
	v_sub_f32_e32 v2, v121, v175
	v_add_f32_e32 v1, v6, v1
	v_cvt_pk_bf16_f32 v73, v3, v4
	v_exp_f32_e32 v2, v2
	v_sub_f32_e32 v3, v122, v175
	v_add_f32_e32 v1, v7, v1
	v_exp_f32_e32 v3, v3
	v_sub_f32_e32 v4, v123, v175
	v_add_f32_e32 v1, v8, v1
	v_cvt_pk_bf16_f32 v74, v5, v6
	v_exp_f32_e32 v4, v4
	v_sub_f32_e32 v5, v124, v175
	v_add_f32_e32 v1, v0, v1
	v_exp_f32_e32 v5, v5
	v_sub_f32_e32 v6, v125, v175
	v_cvt_pk_bf16_f32 v75, v7, v8
	v_add_f32_e32 v1, v2, v1
	v_exp_f32_e32 v6, v6
	v_sub_f32_e32 v7, v126, v175
	v_add_f32_e32 v1, v3, v1
	v_exp_f32_e32 v7, v7
	v_sub_f32_e32 v8, v127, v175
	v_add_f32_e32 v1, v4, v1
	v_exp_f32_e32 v8, v8
	v_add_f32_e32 v1, v5, v1
	v_add_f32_e32 v1, v6, v1
	v_add_f32_e32 v1, v7, v1
	v_add_f32_e32 v88, v8, v1
	v_cvt_pk_bf16_f32 v64, v0, v2
	v_bfe_u32 v0, v172, 2, 2
	v_lshlrev_b32_e32 v1, 1, v172
	v_cvt_pk_bf16_f32 v65, v3, v4
	v_cvt_pk_bf16_f32 v66, v5, v6
	v_lshlrev_b32_e32 v4, 6, v0
	v_and_b32_e32 v5, 32, v1
	v_lshlrev_b32_e32 v1, 3, v172
	v_lshlrev_b32_e32 v0, 8, v0
	v_and_b32_e32 v1, 24, v1
	v_lshl_or_b32 v0, v173, 10, v0
	v_or_b32_e32 v2, v4, v5
	v_add3_u32 v6, s11, v1, v0
	v_add_u32_e32 v92, v6, v2
	ds_read_b64_tr_b16 v[0:1], v92
	ds_read_b64_tr_b16 v[2:3], v92 offset:2048
	v_cvt_pk_bf16_f32 v163, v51, v52
	v_cvt_pk_bf16_f32 v164, v53, v54
	v_cvt_pk_bf16_f32 v165, v55, v56
	s_waitcnt lgkmcnt(0)
	v_mfma_f32_32x32x16_bf16 v[48:63], v[0:3], v[166:169], 0
	v_or_b32_e32 v0, 64, v5
	v_xad_u32 v93, v0, v4, v6
	ds_read_b64_tr_b16 v[0:1], v93
	ds_read_b64_tr_b16 v[2:3], v93 offset:2048
	v_cvt_pk_bf16_f32 v155, v35, v36
	v_cvt_pk_bf16_f32 v156, v37, v38
	v_cvt_pk_bf16_f32 v157, v39, v40
	v_cvt_pk_bf16_f32 v147, v19, v20
	s_waitcnt lgkmcnt(0)
	v_mfma_f32_32x32x16_bf16 v[32:47], v[0:3], v[166:169], 0
	v_or_b32_e32 v0, 0x80, v5
	v_xad_u32 v90, v0, v4, v6
	ds_read_b64_tr_b16 v[0:1], v90
	ds_read_b64_tr_b16 v[2:3], v90 offset:2048
	v_cvt_pk_bf16_f32 v148, v21, v22
	v_cvt_pk_bf16_f32 v149, v23, v24
	v_cvt_pk_bf16_f32 v67, v7, v8
	ds_bpermute_b32 v89, v174, v88
	s_waitcnt lgkmcnt(1)
	v_mfma_f32_32x32x16_bf16 v[16:31], v[0:3], v[166:169], 0
	v_or_b32_e32 v0, 0xc0, v5
	v_xad_u32 v91, v0, v4, v6
	ds_read_b64_tr_b16 v[0:1], v91
	ds_read_b64_tr_b16 v[2:3], v91 offset:2048
	ds_read_b64_tr_b16 v[94:95], v92 offset:4096
	ds_read_b64_tr_b16 v[96:97], v92 offset:6144
	s_waitcnt lgkmcnt(0)
	v_mfma_f32_32x32x16_bf16 v[48:63], v[94:97], v[162:165], v[48:63]
	ds_read_b64_tr_b16 v[94:95], v93 offset:4096
	ds_read_b64_tr_b16 v[96:97], v93 offset:6144
	s_waitcnt lgkmcnt(0)
	v_mfma_f32_32x32x16_bf16 v[32:47], v[94:97], v[162:165], v[32:47]
	ds_read_b64_tr_b16 v[94:95], v90 offset:4096
	ds_read_b64_tr_b16 v[96:97], v90 offset:6144
	v_mfma_f32_32x32x16_bf16 v[0:15], v[0:3], v[166:169], 0
	s_waitcnt lgkmcnt(0)
	v_mfma_f32_32x32x16_bf16 v[16:31], v[94:97], v[162:165], v[16:31]
	ds_read_b64_tr_b16 v[94:95], v91 offset:4096
	ds_read_b64_tr_b16 v[96:97], v91 offset:6144
	s_waitcnt lgkmcnt(0)
	v_mfma_f32_32x32x16_bf16 v[0:15], v[94:97], v[162:165], v[0:15]
	ds_read_b64_tr_b16 v[94:95], v92 offset:8192
	ds_read_b64_tr_b16 v[96:97], v92 offset:10240
	s_waitcnt lgkmcnt(0)
	v_mfma_f32_32x32x16_bf16 v[48:63], v[94:97], v[158:161], v[48:63]
	ds_read_b64_tr_b16 v[94:95], v93 offset:8192
	ds_read_b64_tr_b16 v[96:97], v93 offset:10240
	s_waitcnt lgkmcnt(0)
	v_mfma_f32_32x32x16_bf16 v[32:47], v[94:97], v[158:161], v[32:47]
	ds_read_b64_tr_b16 v[94:95], v90 offset:8192
	ds_read_b64_tr_b16 v[96:97], v90 offset:10240
	s_waitcnt lgkmcnt(0)
	v_mfma_f32_32x32x16_bf16 v[16:31], v[94:97], v[158:161], v[16:31]
	ds_read_b64_tr_b16 v[94:95], v91 offset:8192
	ds_read_b64_tr_b16 v[96:97], v91 offset:10240
	s_waitcnt lgkmcnt(0)
	v_mfma_f32_32x32x16_bf16 v[0:15], v[94:97], v[158:161], v[0:15]
	ds_read_b64_tr_b16 v[94:95], v92 offset:12288
	ds_read_b64_tr_b16 v[96:97], v92 offset:14336
	s_waitcnt lgkmcnt(0)
	v_mfma_f32_32x32x16_bf16 v[48:63], v[94:97], v[154:157], v[48:63]
	ds_read_b64_tr_b16 v[94:95], v93 offset:12288
	ds_read_b64_tr_b16 v[96:97], v93 offset:14336
	s_waitcnt lgkmcnt(0)
	v_mfma_f32_32x32x16_bf16 v[32:47], v[94:97], v[154:157], v[32:47]
	ds_read_b64_tr_b16 v[94:95], v90 offset:12288
	ds_read_b64_tr_b16 v[96:97], v90 offset:14336
	s_waitcnt lgkmcnt(0)
	v_mfma_f32_32x32x16_bf16 v[16:31], v[94:97], v[154:157], v[16:31]
	ds_read_b64_tr_b16 v[94:95], v91 offset:12288
	ds_read_b64_tr_b16 v[96:97], v91 offset:14336
	s_waitcnt lgkmcnt(0)
	v_mfma_f32_32x32x16_bf16 v[0:15], v[94:97], v[154:157], v[0:15]
	ds_read_b64_tr_b16 v[94:95], v92 offset:16384
	ds_read_b64_tr_b16 v[96:97], v92 offset:18432
	s_waitcnt lgkmcnt(0)
	v_mfma_f32_32x32x16_bf16 v[48:63], v[94:97], v[150:153], v[48:63]
	ds_read_b64_tr_b16 v[94:95], v93 offset:16384
	ds_read_b64_tr_b16 v[96:97], v93 offset:18432
	s_waitcnt lgkmcnt(0)
	v_mfma_f32_32x32x16_bf16 v[32:47], v[94:97], v[150:153], v[32:47]
	ds_read_b64_tr_b16 v[94:95], v90 offset:16384
	ds_read_b64_tr_b16 v[96:97], v90 offset:18432
	s_waitcnt lgkmcnt(0)
	v_mfma_f32_32x32x16_bf16 v[16:31], v[94:97], v[150:153], v[16:31]
	ds_read_b64_tr_b16 v[94:95], v91 offset:16384
	ds_read_b64_tr_b16 v[96:97], v91 offset:18432
	s_waitcnt lgkmcnt(0)
	v_mfma_f32_32x32x16_bf16 v[0:15], v[94:97], v[150:153], v[0:15]
	ds_read_b64_tr_b16 v[94:95], v92 offset:20480
	ds_read_b64_tr_b16 v[96:97], v92 offset:22528
	s_waitcnt lgkmcnt(0)
	v_mfma_f32_32x32x16_bf16 v[48:63], v[94:97], v[146:149], v[48:63]
	ds_read_b64_tr_b16 v[94:95], v93 offset:20480
	ds_read_b64_tr_b16 v[96:97], v93 offset:22528
	s_waitcnt lgkmcnt(0)
	v_mfma_f32_32x32x16_bf16 v[32:47], v[94:97], v[146:149], v[32:47]
	ds_read_b64_tr_b16 v[94:95], v90 offset:20480
	ds_read_b64_tr_b16 v[96:97], v90 offset:22528
	s_waitcnt lgkmcnt(0)
	v_mfma_f32_32x32x16_bf16 v[16:31], v[94:97], v[146:149], v[16:31]
	ds_read_b64_tr_b16 v[94:95], v91 offset:20480
	ds_read_b64_tr_b16 v[96:97], v91 offset:22528
	s_waitcnt lgkmcnt(0)
	v_mfma_f32_32x32x16_bf16 v[0:15], v[94:97], v[146:149], v[0:15]
	ds_read_b64_tr_b16 v[94:95], v92 offset:24576
	ds_read_b64_tr_b16 v[96:97], v92 offset:26624
	s_waitcnt lgkmcnt(0)
	v_mfma_f32_32x32x16_bf16 v[48:63], v[94:97], v[142:145], v[48:63]
	ds_read_b64_tr_b16 v[94:95], v93 offset:24576
	ds_read_b64_tr_b16 v[96:97], v93 offset:26624
	s_waitcnt lgkmcnt(0)
	v_mfma_f32_32x32x16_bf16 v[32:47], v[94:97], v[142:145], v[32:47]
	ds_read_b64_tr_b16 v[94:95], v90 offset:24576
	ds_read_b64_tr_b16 v[96:97], v90 offset:26624
	s_waitcnt lgkmcnt(0)
	v_mfma_f32_32x32x16_bf16 v[16:31], v[94:97], v[142:145], v[16:31]
	ds_read_b64_tr_b16 v[94:95], v91 offset:24576
	ds_read_b64_tr_b16 v[96:97], v91 offset:26624
	s_waitcnt lgkmcnt(0)
	v_mfma_f32_32x32x16_bf16 v[0:15], v[94:97], v[142:145], v[0:15]
	ds_read_b64_tr_b16 v[94:95], v92 offset:28672
	ds_read_b64_tr_b16 v[96:97], v92 offset:30720
	s_waitcnt lgkmcnt(0)
	v_mfma_f32_32x32x16_bf16 v[48:63], v[94:97], v[138:141], v[48:63]
	ds_read_b64_tr_b16 v[94:95], v93 offset:28672
	ds_read_b64_tr_b16 v[96:97], v93 offset:30720
	s_waitcnt lgkmcnt(0)
	v_mfma_f32_32x32x16_bf16 v[32:47], v[94:97], v[138:141], v[32:47]
	ds_read_b64_tr_b16 v[94:95], v90 offset:28672
	ds_read_b64_tr_b16 v[96:97], v90 offset:30720
	s_waitcnt lgkmcnt(0)
	v_mfma_f32_32x32x16_bf16 v[16:31], v[94:97], v[138:141], v[16:31]
	ds_read_b64_tr_b16 v[94:95], v91 offset:28672
	ds_read_b64_tr_b16 v[96:97], v91 offset:30720
	s_waitcnt lgkmcnt(0)
	v_mfma_f32_32x32x16_bf16 v[0:15], v[94:97], v[138:141], v[0:15]
	ds_read_b64_tr_b16 v[94:95], v92 offset:32768
	ds_read_b64_tr_b16 v[96:97], v92 offset:34816
	s_waitcnt lgkmcnt(0)
	v_mfma_f32_32x32x16_bf16 v[48:63], v[94:97], v[134:137], v[48:63]
	ds_read_b64_tr_b16 v[94:95], v93 offset:32768
	ds_read_b64_tr_b16 v[96:97], v93 offset:34816
	s_waitcnt lgkmcnt(0)
	v_mfma_f32_32x32x16_bf16 v[32:47], v[94:97], v[134:137], v[32:47]
	ds_read_b64_tr_b16 v[94:95], v90 offset:32768
	ds_read_b64_tr_b16 v[96:97], v90 offset:34816
	s_waitcnt lgkmcnt(0)
	v_mfma_f32_32x32x16_bf16 v[16:31], v[94:97], v[134:137], v[16:31]
	ds_read_b64_tr_b16 v[94:95], v91 offset:32768
	ds_read_b64_tr_b16 v[96:97], v91 offset:34816
	s_waitcnt lgkmcnt(0)
	v_mfma_f32_32x32x16_bf16 v[0:15], v[94:97], v[134:137], v[0:15]
	ds_read_b64_tr_b16 v[94:95], v92 offset:36864
	ds_read_b64_tr_b16 v[96:97], v92 offset:38912
	s_waitcnt lgkmcnt(0)
	v_mfma_f32_32x32x16_bf16 v[48:63], v[94:97], v[130:133], v[48:63]
	ds_read_b64_tr_b16 v[94:95], v93 offset:36864
	ds_read_b64_tr_b16 v[96:97], v93 offset:38912
	s_waitcnt lgkmcnt(0)
	v_mfma_f32_32x32x16_bf16 v[32:47], v[94:97], v[130:133], v[32:47]
	ds_read_b64_tr_b16 v[94:95], v90 offset:36864
	ds_read_b64_tr_b16 v[96:97], v90 offset:38912
	s_waitcnt lgkmcnt(0)
	v_mfma_f32_32x32x16_bf16 v[16:31], v[94:97], v[130:133], v[16:31]
	ds_read_b64_tr_b16 v[94:95], v91 offset:36864
	ds_read_b64_tr_b16 v[96:97], v91 offset:38912
	s_waitcnt lgkmcnt(0)
	v_mfma_f32_32x32x16_bf16 v[0:15], v[94:97], v[130:133], v[0:15]
	ds_read_b64_tr_b16 v[94:95], v92 offset:40960
	ds_read_b64_tr_b16 v[96:97], v92 offset:43008
	s_waitcnt lgkmcnt(0)
	v_mfma_f32_32x32x16_bf16 v[48:63], v[94:97], v[84:87], v[48:63]
	ds_read_b64_tr_b16 v[94:95], v93 offset:40960
	ds_read_b64_tr_b16 v[96:97], v93 offset:43008
	s_waitcnt lgkmcnt(0)
	v_mfma_f32_32x32x16_bf16 v[32:47], v[94:97], v[84:87], v[32:47]
	ds_read_b64_tr_b16 v[94:95], v90 offset:40960
	ds_read_b64_tr_b16 v[96:97], v90 offset:43008
	s_waitcnt lgkmcnt(0)
	v_mfma_f32_32x32x16_bf16 v[16:31], v[94:97], v[84:87], v[16:31]
	ds_read_b64_tr_b16 v[94:95], v91 offset:40960
	ds_read_b64_tr_b16 v[96:97], v91 offset:43008
	s_waitcnt lgkmcnt(0)
	v_mfma_f32_32x32x16_bf16 v[0:15], v[94:97], v[84:87], v[0:15]
	ds_read_b64_tr_b16 v[84:85], v92 offset:45056
	ds_read_b64_tr_b16 v[86:87], v92 offset:47104
	s_waitcnt lgkmcnt(0)
	v_mfma_f32_32x32x16_bf16 v[48:63], v[84:87], v[80:83], v[48:63]
	ds_read_b64_tr_b16 v[84:85], v93 offset:45056
	ds_read_b64_tr_b16 v[86:87], v93 offset:47104
	s_waitcnt lgkmcnt(0)
	v_mfma_f32_32x32x16_bf16 v[32:47], v[84:87], v[80:83], v[32:47]
	ds_read_b64_tr_b16 v[84:85], v90 offset:45056
	ds_read_b64_tr_b16 v[86:87], v90 offset:47104
	s_waitcnt lgkmcnt(0)
	v_mfma_f32_32x32x16_bf16 v[16:31], v[84:87], v[80:83], v[16:31]
	ds_read_b64_tr_b16 v[84:85], v91 offset:45056
	ds_read_b64_tr_b16 v[86:87], v91 offset:47104
	s_waitcnt lgkmcnt(0)
	v_mfma_f32_32x32x16_bf16 v[0:15], v[84:87], v[80:83], v[0:15]
	ds_read_b64_tr_b16 v[80:81], v92 offset:49152
	ds_read_b64_tr_b16 v[82:83], v92 offset:51200
	s_waitcnt lgkmcnt(0)
	v_mfma_f32_32x32x16_bf16 v[48:63], v[80:83], v[76:79], v[48:63]
	ds_read_b64_tr_b16 v[80:81], v93 offset:49152
	ds_read_b64_tr_b16 v[82:83], v93 offset:51200
	s_waitcnt lgkmcnt(0)
	v_mfma_f32_32x32x16_bf16 v[32:47], v[80:83], v[76:79], v[32:47]
	ds_read_b64_tr_b16 v[80:81], v90 offset:49152
	ds_read_b64_tr_b16 v[82:83], v90 offset:51200
	s_waitcnt lgkmcnt(0)
	v_mfma_f32_32x32x16_bf16 v[16:31], v[80:83], v[76:79], v[16:31]
	ds_read_b64_tr_b16 v[80:81], v91 offset:49152
	ds_read_b64_tr_b16 v[82:83], v91 offset:51200
	s_waitcnt lgkmcnt(0)
	v_mfma_f32_32x32x16_bf16 v[0:15], v[80:83], v[76:79], v[0:15]
	ds_read_b64_tr_b16 v[76:77], v92 offset:53248
	ds_read_b64_tr_b16 v[78:79], v92 offset:55296
	s_waitcnt lgkmcnt(0)
	v_mfma_f32_32x32x16_bf16 v[48:63], v[76:79], v[68:71], v[48:63]
	ds_read_b64_tr_b16 v[76:77], v93 offset:53248
	ds_read_b64_tr_b16 v[78:79], v93 offset:55296
	s_waitcnt lgkmcnt(0)
	v_mfma_f32_32x32x16_bf16 v[32:47], v[76:79], v[68:71], v[32:47]
	ds_read_b64_tr_b16 v[76:77], v90 offset:53248
	ds_read_b64_tr_b16 v[78:79], v90 offset:55296
	s_waitcnt lgkmcnt(0)
	v_mfma_f32_32x32x16_bf16 v[16:31], v[76:79], v[68:71], v[16:31]
	ds_read_b64_tr_b16 v[76:77], v91 offset:53248
	ds_read_b64_tr_b16 v[78:79], v91 offset:55296
	s_waitcnt lgkmcnt(0)
	v_mfma_f32_32x32x16_bf16 v[0:15], v[76:79], v[68:71], v[0:15]
	ds_read_b64_tr_b16 v[68:69], v92 offset:57344
	ds_read_b64_tr_b16 v[70:71], v92 offset:59392
	s_waitcnt lgkmcnt(0)
	v_mfma_f32_32x32x16_bf16 v[48:63], v[68:71], v[72:75], v[48:63]
	ds_read_b64_tr_b16 v[68:69], v93 offset:57344
	ds_read_b64_tr_b16 v[70:71], v93 offset:59392
	s_waitcnt lgkmcnt(0)
	v_mfma_f32_32x32x16_bf16 v[32:47], v[68:71], v[72:75], v[32:47]
	ds_read_b64_tr_b16 v[68:69], v90 offset:57344
	ds_read_b64_tr_b16 v[70:71], v90 offset:59392
	s_waitcnt lgkmcnt(0)
	v_mfma_f32_32x32x16_bf16 v[16:31], v[68:71], v[72:75], v[16:31]
	ds_read_b64_tr_b16 v[68:69], v91 offset:57344
	ds_read_b64_tr_b16 v[70:71], v91 offset:59392
	s_waitcnt lgkmcnt(0)
	v_mfma_f32_32x32x16_bf16 v[0:15], v[68:71], v[72:75], v[0:15]
	ds_read_b64_tr_b16 v[68:69], v92 offset:61440
	ds_read_b64_tr_b16 v[70:71], v92 offset:63488
	s_waitcnt lgkmcnt(0)
	v_mfma_f32_32x32x16_bf16 v[48:63], v[68:71], v[64:67], v[48:63]
	ds_read_b64_tr_b16 v[68:69], v93 offset:61440
	ds_read_b64_tr_b16 v[70:71], v93 offset:63488
	s_waitcnt lgkmcnt(0)
	v_mfma_f32_32x32x16_bf16 v[32:47], v[68:71], v[64:67], v[32:47]
	ds_read_b64_tr_b16 v[68:69], v90 offset:61440
	ds_read_b64_tr_b16 v[70:71], v90 offset:63488
	s_waitcnt lgkmcnt(0)
	v_mfma_f32_32x32x16_bf16 v[16:31], v[68:71], v[64:67], v[16:31]
	ds_read_b64_tr_b16 v[68:69], v91 offset:61440
	ds_read_b64_tr_b16 v[70:71], v91 offset:63488
	s_waitcnt lgkmcnt(0)
	v_mfma_f32_32x32x16_bf16 v[0:15], v[68:71], v[64:67], v[0:15]
	v_add_f32_e32 v64, v88, v89
	v_div_scale_f32 v65, s[4:5], v64, v64, 1.0
	v_rcp_f32_e32 v66, v65
	v_readlane_b32 s4, v237, 38
	s_add_i32 s9, s9, s4
	v_readlane_b32 s4, v237, 58
	v_fma_f32 v67, -v65, v66, 1.0
	v_fmac_f32_e32 v66, v67, v66
	v_div_scale_f32 v67, vcc, 1.0, v64, 1.0
	v_mul_f32_e32 v68, v67, v66
	v_fma_f32 v69, -v65, v68, v67
	v_fmac_f32_e32 v68, v69, v66
	v_fma_f32 v65, -v65, v68, v67
	v_div_fmas_f32 v65, v65, v66, v68
	v_div_fixup_f32 v64, v65, v64, 1.0
	v_pk_mul_f32 v[48:49], v[64:65], v[48:49] op_sel_hi:[0,1]
	v_pk_mul_f32 v[50:51], v[64:65], v[50:51] op_sel_hi:[0,1]
	v_pk_mul_f32 v[32:33], v[64:65], v[32:33] op_sel_hi:[0,1]
	v_pk_mul_f32 v[34:35], v[64:65], v[34:35] op_sel_hi:[0,1]
	v_pk_mul_f32 v[16:17], v[64:65], v[16:17] op_sel_hi:[0,1]
	v_pk_mul_f32 v[18:19], v[64:65], v[18:19] op_sel_hi:[0,1]
	v_pk_mul_f32 v[0:1], v[64:65], v[0:1] op_sel_hi:[0,1]
	v_pk_mul_f32 v[2:3], v[64:65], v[2:3] op_sel_hi:[0,1]
	v_lshl_add_u64 v[66:67], v[170:171], 0, v[128:129]
	v_cvt_pk_bf16_f32 v48, v48, v49
	v_cvt_pk_bf16_f32 v49, v50, v51
	v_cvt_pk_bf16_f32 v32, v32, v33
	v_cvt_pk_bf16_f32 v33, v34, v35
	v_cvt_pk_bf16_f32 v16, v16, v17
	v_cvt_pk_bf16_f32 v17, v18, v19
	v_cvt_pk_bf16_f32 v0, v0, v1
	v_cvt_pk_bf16_f32 v1, v2, v3
	global_store_dwordx2 v[66:67], v[48:49], off
	v_pk_mul_f32 v[48:49], v[64:65], v[52:53] op_sel_hi:[0,1]
	v_pk_mul_f32 v[50:51], v[64:65], v[54:55] op_sel_hi:[0,1]
	global_store_dwordx2 v[66:67], v[32:33], off offset:64
	v_pk_mul_f32 v[32:33], v[64:65], v[36:37] op_sel_hi:[0,1]
	v_pk_mul_f32 v[34:35], v[64:65], v[38:39] op_sel_hi:[0,1]
	global_store_dwordx2 v[66:67], v[16:17], off offset:128
	v_pk_mul_f32 v[16:17], v[64:65], v[20:21] op_sel_hi:[0,1]
	v_pk_mul_f32 v[18:19], v[64:65], v[22:23] op_sel_hi:[0,1]
	global_store_dwordx2 v[66:67], v[0:1], off offset:192
	v_pk_mul_f32 v[0:1], v[64:65], v[4:5] op_sel_hi:[0,1]
	v_pk_mul_f32 v[2:3], v[64:65], v[6:7] op_sel_hi:[0,1]
	v_cvt_pk_bf16_f32 v48, v48, v49
	v_cvt_pk_bf16_f32 v49, v50, v51
	v_cvt_pk_bf16_f32 v32, v32, v33
	v_cvt_pk_bf16_f32 v33, v34, v35
	v_cvt_pk_bf16_f32 v16, v16, v17
	v_cvt_pk_bf16_f32 v17, v18, v19
	v_cvt_pk_bf16_f32 v0, v0, v1
	v_cvt_pk_bf16_f32 v1, v2, v3
	global_store_dwordx2 v[66:67], v[48:49], off offset:16
	v_pk_mul_f32 v[48:49], v[64:65], v[56:57] op_sel_hi:[0,1]
	v_pk_mul_f32 v[50:51], v[64:65], v[58:59] op_sel_hi:[0,1]
	global_store_dwordx2 v[66:67], v[32:33], off offset:80
	v_pk_mul_f32 v[32:33], v[64:65], v[40:41] op_sel_hi:[0,1]
	v_pk_mul_f32 v[34:35], v[64:65], v[42:43] op_sel_hi:[0,1]
	global_store_dwordx2 v[66:67], v[16:17], off offset:144
	v_pk_mul_f32 v[16:17], v[64:65], v[24:25] op_sel_hi:[0,1]
	v_pk_mul_f32 v[18:19], v[64:65], v[26:27] op_sel_hi:[0,1]
	global_store_dwordx2 v[66:67], v[0:1], off offset:208
	v_pk_mul_f32 v[0:1], v[64:65], v[8:9] op_sel_hi:[0,1]
	v_pk_mul_f32 v[2:3], v[64:65], v[10:11] op_sel_hi:[0,1]
	v_cvt_pk_bf16_f32 v48, v48, v49
	v_cvt_pk_bf16_f32 v49, v50, v51
	v_cvt_pk_bf16_f32 v32, v32, v33
	v_cvt_pk_bf16_f32 v33, v34, v35
	v_cvt_pk_bf16_f32 v16, v16, v17
	v_cvt_pk_bf16_f32 v17, v18, v19
	v_cvt_pk_bf16_f32 v0, v0, v1
	v_cvt_pk_bf16_f32 v1, v2, v3
	global_store_dwordx2 v[66:67], v[48:49], off offset:32
	v_pk_mul_f32 v[48:49], v[64:65], v[60:61] op_sel_hi:[0,1]
	v_pk_mul_f32 v[50:51], v[64:65], v[62:63] op_sel_hi:[0,1]
	global_store_dwordx2 v[66:67], v[32:33], off offset:96
	v_pk_mul_f32 v[32:33], v[64:65], v[44:45] op_sel_hi:[0,1]
	v_pk_mul_f32 v[34:35], v[64:65], v[46:47] op_sel_hi:[0,1]
	global_store_dwordx2 v[66:67], v[16:17], off offset:160
	v_pk_mul_f32 v[16:17], v[64:65], v[28:29] op_sel_hi:[0,1]
	v_pk_mul_f32 v[18:19], v[64:65], v[30:31] op_sel_hi:[0,1]
	global_store_dwordx2 v[66:67], v[0:1], off offset:224
	v_pk_mul_f32 v[0:1], v[64:65], v[12:13] op_sel_hi:[0,1]
	v_pk_mul_f32 v[2:3], v[64:65], v[14:15] op_sel_hi:[0,1]
	s_add_i32 s8, s8, s4
	v_cvt_pk_bf16_f32 v48, v48, v49
	v_cvt_pk_bf16_f32 v49, v50, v51
	v_cvt_pk_bf16_f32 v32, v32, v33
	v_cvt_pk_bf16_f32 v33, v34, v35
	v_cvt_pk_bf16_f32 v16, v16, v17
	v_cvt_pk_bf16_f32 v17, v18, v19
	v_cvt_pk_bf16_f32 v0, v0, v1
	v_cvt_pk_bf16_f32 v1, v2, v3
	s_cmpk_gt_i32 s10, 0x7f
	global_store_dwordx2 v[66:67], v[48:49], off offset:48
	global_store_dwordx2 v[66:67], v[32:33], off offset:112
	global_store_dwordx2 v[66:67], v[16:17], off offset:176
	global_store_dwordx2 v[66:67], v[0:1], off offset:240
	s_cbranch_scc1 .LBB0_1308
